# residual GEMM epilogues (out-proj, down-proj): residual rows prefetched 3 row-groups ahead with counted waits instead of load/vmcnt(0)/store per half group
# speedup vs baseline: 1.0480x; 1.0121x over previous
.LBB0_568:
	s_add_u32 s36, s28, 0xfffc0080
	s_addc_u32 s37, s29, -1
	s_add_i32 s68, s44, 0x120
	s_cmp_eq_u32 s67, 12
	s_cselect_b32 s39, s23, s37
	s_cselect_b32 s38, s61, s36
	v_add_u32_e32 v142, s68, v145
	s_cselect_b32 s37, s21, s66
	s_cselect_b32 s36, s62, s63
	s_add_i32 s70, s45, 0x120
	ds_read_b128 v[138:141], v142
	ds_read_b128 v[148:151], v142 offset:1024
	ds_read_b128 v[152:155], v142 offset:2048
	ds_read_b128 v[156:159], v142 offset:3072
	v_add_u32_e32 v142, s70, v145
	ds_read_b128 v[200:203], v142
	ds_read_b128 v[204:207], v142 offset:1024
	ds_read_b128 v[208:211], v142 offset:2048
	ds_read_b128 v[212:215], v142 offset:3072
	v_lshl_add_u64 v[142:143], s[28:29], 0, v[134:135]
	s_add_i32 m0, s52, 0xc000
	ds_read_b128 v[216:219], v147
	ds_read_b128 v[220:223], v147 offset:1024
	ds_read_b128 v[224:227], v147 offset:2048
	ds_read_b128 v[228:231], v147 offset:3072
	ds_read_b128 v[232:235], v147 offset:4096
	ds_read_b128 v[236:239], v147 offset:5120
	ds_read_b128 v[240:243], v147 offset:6144
	ds_read_b128 v[244:247], v147 offset:7168
	global_load_lds_dwordx4 v[142:143], off
	v_lshl_add_u64 v[142:143], s[28:29], 0, v[136:137]
	s_add_i32 m0, s52, 0xe000
	s_nop 0
	global_load_lds_dwordx4 v[142:143], off
	s_waitcnt vmcnt(8)
	s_waitcnt lgkmcnt(0)
	s_barrier
	s_setprio 1
	s_waitcnt lgkmcnt(0)
	v_mfma_f32_16x16x32_bf16 v[124:127], v[138:141], v[216:219], v[124:127]
	v_mfma_f32_16x16x32_bf16 v[120:123], v[152:155], v[216:219], v[120:123]
	v_mfma_f32_16x16x32_bf16 v[108:111], v[138:141], v[224:227], v[108:111]
	v_mfma_f32_16x16x32_bf16 v[104:107], v[152:155], v[224:227], v[104:107]
	v_mfma_f32_16x16x32_bf16 v[92:95], v[138:141], v[232:235], v[92:95]
	v_mfma_f32_16x16x32_bf16 v[88:91], v[152:155], v[232:235], v[88:91]
	v_mfma_f32_16x16x32_bf16 v[76:79], v[138:141], v[240:243], v[76:79]
	v_mfma_f32_16x16x32_bf16 v[72:75], v[152:155], v[240:243], v[72:75]
	v_mfma_f32_16x16x32_bf16 v[124:127], v[148:151], v[220:223], v[124:127]
	v_mfma_f32_16x16x32_bf16 v[120:123], v[156:159], v[220:223], v[120:123]
	v_mfma_f32_16x16x32_bf16 v[108:111], v[148:151], v[228:231], v[108:111]
	v_mfma_f32_16x16x32_bf16 v[104:107], v[156:159], v[228:231], v[104:107]
	v_mfma_f32_16x16x32_bf16 v[92:95], v[148:151], v[236:239], v[92:95]
	v_mfma_f32_16x16x32_bf16 v[88:91], v[156:159], v[236:239], v[88:91]
	v_mfma_f32_16x16x32_bf16 v[76:79], v[148:151], v[244:247], v[76:79]
	v_mfma_f32_16x16x32_bf16 v[72:75], v[156:159], v[244:247], v[72:75]
	s_setprio 0
	s_setprio 1
	v_mfma_f32_16x16x32_bf16 v[116:119], v[200:203], v[216:219], v[116:119]
	v_mfma_f32_16x16x32_bf16 v[112:115], v[208:211], v[216:219], v[112:115]
	v_mfma_f32_16x16x32_bf16 v[100:103], v[200:203], v[224:227], v[100:103]
	v_mfma_f32_16x16x32_bf16 v[96:99], v[208:211], v[224:227], v[96:99]
	v_mfma_f32_16x16x32_bf16 v[84:87], v[200:203], v[232:235], v[84:87]
	v_mfma_f32_16x16x32_bf16 v[80:83], v[208:211], v[232:235], v[80:83]
	v_mfma_f32_16x16x32_bf16 v[68:71], v[200:203], v[240:243], v[68:71]
	v_mfma_f32_16x16x32_bf16 v[64:67], v[208:211], v[240:243], v[64:67]
	v_mfma_f32_16x16x32_bf16 v[116:119], v[204:207], v[220:223], v[116:119]
	v_mfma_f32_16x16x32_bf16 v[112:115], v[212:215], v[220:223], v[112:115]
	v_mfma_f32_16x16x32_bf16 v[100:103], v[204:207], v[228:231], v[100:103]
	v_mfma_f32_16x16x32_bf16 v[96:99], v[212:215], v[228:231], v[96:99]
	v_mfma_f32_16x16x32_bf16 v[84:87], v[204:207], v[236:239], v[84:87]
	v_mfma_f32_16x16x32_bf16 v[80:83], v[212:215], v[236:239], v[80:83]
	v_mfma_f32_16x16x32_bf16 v[68:71], v[204:207], v[244:247], v[68:71]
	v_mfma_f32_16x16x32_bf16 v[64:67], v[212:215], v[244:247], v[64:67]
	s_setprio 0
	s_barrier
	s_add_i32 s68, s68, s49
	v_lshl_add_u64 v[142:143], s[36:37], 0, v[160:161]
	s_mov_b32 m0, s68
	ds_read_b128 v[216:219], v147 offset:16384
	ds_read_b128 v[220:223], v147 offset:17408
	ds_read_b128 v[224:227], v147 offset:18432
	ds_read_b128 v[228:231], v147 offset:19456
	ds_read_b128 v[232:235], v147 offset:20480
	ds_read_b128 v[236:239], v147 offset:21504
	ds_read_b128 v[240:243], v147 offset:22528
	ds_read_b128 v[244:247], v147 offset:23552
	global_load_lds_dwordx4 v[142:143], off
	s_add_i32 m0, s68, 0x2000
	s_add_u32 s68, s36, 0x40000
	v_lshl_add_u64 v[170:171], s[36:37], 0, v[128:129]
	s_addc_u32 s69, s37, 0
	s_add_i32 s70, s70, s49
	global_load_lds_dwordx4 v[170:171], off
	v_lshl_add_u64 v[174:175], s[68:69], 0, v[160:161]
	s_mov_b32 m0, s70
	v_lshl_add_u64 v[198:199], s[38:39], 0, v[130:131]
	global_load_lds_dwordx4 v[174:175], off
	v_lshl_add_u64 v[174:175], s[68:69], 0, v[128:129]
	s_add_i32 m0, s70, 0x2000
	s_nop 0
	global_load_lds_dwordx4 v[174:175], off
	v_lshl_add_u64 v[174:175], s[38:39], 0, v[132:133]
	s_mov_b32 m0, s52
	s_nop 0
	global_load_lds_dwordx4 v[174:175], off
	s_mov_b32 m0, s53
	s_nop 0
	global_load_lds_dwordx4 v[198:199], off
	s_waitcnt vmcnt(8)
	s_waitcnt lgkmcnt(0)
	s_barrier
	s_setprio 1
	s_waitcnt lgkmcnt(0)
	v_mfma_f32_16x16x32_bf16 v[60:63], v[138:141], v[216:219], v[60:63]
	v_mfma_f32_16x16x32_bf16 v[56:59], v[152:155], v[216:219], v[56:59]
	v_mfma_f32_16x16x32_bf16 v[44:47], v[138:141], v[224:227], v[44:47]
	v_mfma_f32_16x16x32_bf16 v[40:43], v[152:155], v[224:227], v[40:43]
	v_mfma_f32_16x16x32_bf16 v[28:31], v[138:141], v[232:235], v[28:31]
	v_mfma_f32_16x16x32_bf16 v[24:27], v[152:155], v[232:235], v[24:27]
	v_mfma_f32_16x16x32_bf16 v[12:15], v[138:141], v[240:243], v[12:15]
	v_mfma_f32_16x16x32_bf16 v[8:11], v[152:155], v[240:243], v[8:11]
	v_mfma_f32_16x16x32_bf16 v[60:63], v[148:151], v[220:223], v[60:63]
	v_mfma_f32_16x16x32_bf16 v[56:59], v[156:159], v[220:223], v[56:59]
	v_mfma_f32_16x16x32_bf16 v[44:47], v[148:151], v[228:231], v[44:47]
	v_mfma_f32_16x16x32_bf16 v[40:43], v[156:159], v[228:231], v[40:43]
	v_mfma_f32_16x16x32_bf16 v[28:31], v[148:151], v[236:239], v[28:31]
	v_mfma_f32_16x16x32_bf16 v[24:27], v[156:159], v[236:239], v[24:27]
	v_mfma_f32_16x16x32_bf16 v[12:15], v[148:151], v[244:247], v[12:15]
	v_mfma_f32_16x16x32_bf16 v[8:11], v[156:159], v[244:247], v[8:11]
	s_setprio 0
	s_setprio 1
	v_mfma_f32_16x16x32_bf16 v[52:55], v[200:203], v[216:219], v[52:55]
	v_mfma_f32_16x16x32_bf16 v[48:51], v[208:211], v[216:219], v[48:51]
	v_mfma_f32_16x16x32_bf16 v[36:39], v[200:203], v[224:227], v[36:39]
	v_mfma_f32_16x16x32_bf16 v[32:35], v[208:211], v[224:227], v[32:35]
	v_mfma_f32_16x16x32_bf16 v[20:23], v[200:203], v[232:235], v[20:23]
	v_mfma_f32_16x16x32_bf16 v[16:19], v[208:211], v[232:235], v[16:19]
	v_mfma_f32_16x16x32_bf16 v[4:7], v[200:203], v[240:243], v[4:7]
	v_mfma_f32_16x16x32_bf16 v[0:3], v[208:211], v[240:243], v[0:3]
	v_mfma_f32_16x16x32_bf16 v[52:55], v[204:207], v[220:223], v[52:55]
	v_mfma_f32_16x16x32_bf16 v[48:51], v[212:215], v[220:223], v[48:51]
	v_mfma_f32_16x16x32_bf16 v[36:39], v[204:207], v[228:231], v[36:39]
	v_mfma_f32_16x16x32_bf16 v[32:35], v[212:215], v[228:231], v[32:35]
	v_mfma_f32_16x16x32_bf16 v[20:23], v[204:207], v[236:239], v[20:23]
	v_mfma_f32_16x16x32_bf16 v[16:19], v[212:215], v[236:239], v[16:19]
	v_mfma_f32_16x16x32_bf16 v[4:7], v[204:207], v[244:247], v[4:7]
	v_mfma_f32_16x16x32_bf16 v[0:3], v[212:215], v[244:247], v[0:3]
	s_setprio 0
	s_barrier
	s_add_i32 s68, s46, 0x120
	s_add_i32 s69, s47, 0x120
	v_add_u32_e32 v156, s68, v145
	v_add_u32_e32 v172, s69, v145
	ds_read_b128 v[138:141], v156
	ds_read_b128 v[148:151], v156 offset:1024
	ds_read_b128 v[152:155], v156 offset:2048
	ds_read_b128 v[156:159], v156 offset:3072
	ds_read_b128 v[200:203], v172
	ds_read_b128 v[204:207], v172 offset:1024
	ds_read_b128 v[208:211], v172 offset:2048
	ds_read_b128 v[212:215], v172 offset:3072
	s_add_u32 s38, s38, 0x40000
	s_addc_u32 s39, s39, 0
	s_mov_b32 m0, s56
	v_lshl_add_u64 v[248:249], s[38:39], 0, v[132:133]
	ds_read_b128 v[216:219], v147 offset:32768
	ds_read_b128 v[220:223], v147 offset:33792
	ds_read_b128 v[224:227], v147 offset:34816
	ds_read_b128 v[228:231], v147 offset:35840
	ds_read_b128 v[232:235], v147 offset:36864
	ds_read_b128 v[236:239], v147 offset:37888
	ds_read_b128 v[240:243], v147 offset:38912
	ds_read_b128 v[244:247], v147 offset:39936
	global_load_lds_dwordx4 v[248:249], off
	v_lshl_add_u64 v[248:249], s[38:39], 0, v[130:131]
	s_mov_b32 m0, s57
	s_nop 0
	global_load_lds_dwordx4 v[248:249], off
	s_waitcnt vmcnt(8)
	s_waitcnt lgkmcnt(0)
	s_barrier
	s_setprio 1
	s_waitcnt lgkmcnt(0)
	v_mfma_f32_16x16x32_bf16 v[124:127], v[138:141], v[216:219], v[124:127]
	v_mfma_f32_16x16x32_bf16 v[120:123], v[152:155], v[216:219], v[120:123]
	v_mfma_f32_16x16x32_bf16 v[108:111], v[138:141], v[224:227], v[108:111]
	v_mfma_f32_16x16x32_bf16 v[104:107], v[152:155], v[224:227], v[104:107]
	v_mfma_f32_16x16x32_bf16 v[92:95], v[138:141], v[232:235], v[92:95]
	v_mfma_f32_16x16x32_bf16 v[88:91], v[152:155], v[232:235], v[88:91]
	v_mfma_f32_16x16x32_bf16 v[76:79], v[138:141], v[240:243], v[76:79]
	v_mfma_f32_16x16x32_bf16 v[72:75], v[152:155], v[240:243], v[72:75]
	v_mfma_f32_16x16x32_bf16 v[124:127], v[148:151], v[220:223], v[124:127]
	v_mfma_f32_16x16x32_bf16 v[120:123], v[156:159], v[220:223], v[120:123]
	v_mfma_f32_16x16x32_bf16 v[108:111], v[148:151], v[228:231], v[108:111]
	v_mfma_f32_16x16x32_bf16 v[104:107], v[156:159], v[228:231], v[104:107]
	v_mfma_f32_16x16x32_bf16 v[92:95], v[148:151], v[236:239], v[92:95]
	v_mfma_f32_16x16x32_bf16 v[88:91], v[156:159], v[236:239], v[88:91]
	v_mfma_f32_16x16x32_bf16 v[76:79], v[148:151], v[244:247], v[76:79]
	v_mfma_f32_16x16x32_bf16 v[72:75], v[156:159], v[244:247], v[72:75]
	s_setprio 0
	s_setprio 1
	v_mfma_f32_16x16x32_bf16 v[116:119], v[200:203], v[216:219], v[116:119]
	v_mfma_f32_16x16x32_bf16 v[112:115], v[208:211], v[216:219], v[112:115]
	v_mfma_f32_16x16x32_bf16 v[100:103], v[200:203], v[224:227], v[100:103]
	v_mfma_f32_16x16x32_bf16 v[96:99], v[208:211], v[224:227], v[96:99]
	v_mfma_f32_16x16x32_bf16 v[84:87], v[200:203], v[232:235], v[84:87]
	v_mfma_f32_16x16x32_bf16 v[80:83], v[208:211], v[232:235], v[80:83]
	v_mfma_f32_16x16x32_bf16 v[68:71], v[200:203], v[240:243], v[68:71]
	v_mfma_f32_16x16x32_bf16 v[64:67], v[208:211], v[240:243], v[64:67]
	v_mfma_f32_16x16x32_bf16 v[116:119], v[204:207], v[220:223], v[116:119]
	v_mfma_f32_16x16x32_bf16 v[112:115], v[212:215], v[220:223], v[112:115]
	v_mfma_f32_16x16x32_bf16 v[100:103], v[204:207], v[228:231], v[100:103]
	v_mfma_f32_16x16x32_bf16 v[96:99], v[212:215], v[228:231], v[96:99]
	v_mfma_f32_16x16x32_bf16 v[84:87], v[204:207], v[236:239], v[84:87]
	v_mfma_f32_16x16x32_bf16 v[80:83], v[212:215], v[236:239], v[80:83]
	v_mfma_f32_16x16x32_bf16 v[68:71], v[204:207], v[244:247], v[68:71]
	v_mfma_f32_16x16x32_bf16 v[64:67], v[212:215], v[244:247], v[64:67]
	s_setprio 0
	s_barrier
	s_add_i32 s38, s68, s49
	v_lshl_add_u64 v[142:143], v[142:143], 0, s[88:89]
	s_mov_b32 m0, s38
	ds_read_b128 v[216:219], v147 offset:49152
	ds_read_b128 v[220:223], v147 offset:50176
	ds_read_b128 v[224:227], v147 offset:51200
	ds_read_b128 v[228:231], v147 offset:52224
	ds_read_b128 v[232:235], v147 offset:53248
	ds_read_b128 v[236:239], v147 offset:54272
	ds_read_b128 v[240:243], v147 offset:55296
	ds_read_b128 v[244:247], v147 offset:56320
	global_load_lds_dwordx4 v[142:143], off
	s_add_i32 m0, s38, 0x2000
	s_add_u32 s36, s36, 0x40080
	v_lshl_add_u64 v[142:143], v[170:171], 0, s[88:89]
	s_addc_u32 s37, s37, 0
	s_add_i32 s38, s69, s49
	global_load_lds_dwordx4 v[142:143], off
	v_lshl_add_u64 v[142:143], s[36:37], 0, v[160:161]
	s_mov_b32 m0, s38
	s_nop 0
	global_load_lds_dwordx4 v[142:143], off
	v_lshl_add_u64 v[142:143], s[36:37], 0, v[128:129]
	s_add_i32 m0, s38, 0x2000
	s_nop 0
	global_load_lds_dwordx4 v[142:143], off
	v_lshl_add_u64 v[142:143], v[174:175], 0, s[88:89]
	s_mov_b32 m0, s58
	s_nop 0
	global_load_lds_dwordx4 v[142:143], off
	v_lshl_add_u64 v[142:143], v[198:199], 0, s[88:89]
	s_mov_b32 m0, s59
	s_nop 0
	global_load_lds_dwordx4 v[142:143], off
	s_waitcnt vmcnt(8)
	s_waitcnt lgkmcnt(0)
	s_barrier
	s_setprio 1
	s_waitcnt lgkmcnt(0)
	v_mfma_f32_16x16x32_bf16 v[60:63], v[138:141], v[216:219], v[60:63]
	v_mfma_f32_16x16x32_bf16 v[56:59], v[152:155], v[216:219], v[56:59]
	v_mfma_f32_16x16x32_bf16 v[44:47], v[138:141], v[224:227], v[44:47]
	v_mfma_f32_16x16x32_bf16 v[40:43], v[152:155], v[224:227], v[40:43]
	v_mfma_f32_16x16x32_bf16 v[28:31], v[138:141], v[232:235], v[28:31]
	v_mfma_f32_16x16x32_bf16 v[24:27], v[152:155], v[232:235], v[24:27]
	v_mfma_f32_16x16x32_bf16 v[12:15], v[138:141], v[240:243], v[12:15]
	v_mfma_f32_16x16x32_bf16 v[8:11], v[152:155], v[240:243], v[8:11]
	v_mfma_f32_16x16x32_bf16 v[60:63], v[148:151], v[220:223], v[60:63]
	v_mfma_f32_16x16x32_bf16 v[56:59], v[156:159], v[220:223], v[56:59]
	v_mfma_f32_16x16x32_bf16 v[44:47], v[148:151], v[228:231], v[44:47]
	v_mfma_f32_16x16x32_bf16 v[40:43], v[156:159], v[228:231], v[40:43]
	v_mfma_f32_16x16x32_bf16 v[28:31], v[148:151], v[236:239], v[28:31]
	v_mfma_f32_16x16x32_bf16 v[24:27], v[156:159], v[236:239], v[24:27]
	v_mfma_f32_16x16x32_bf16 v[12:15], v[148:151], v[244:247], v[12:15]
	v_mfma_f32_16x16x32_bf16 v[8:11], v[156:159], v[244:247], v[8:11]
	s_setprio 0
	s_setprio 1
	v_mfma_f32_16x16x32_bf16 v[52:55], v[200:203], v[216:219], v[52:55]
	v_mfma_f32_16x16x32_bf16 v[48:51], v[208:211], v[216:219], v[48:51]
	v_mfma_f32_16x16x32_bf16 v[36:39], v[200:203], v[224:227], v[36:39]
	v_mfma_f32_16x16x32_bf16 v[32:35], v[208:211], v[224:227], v[32:35]
	v_mfma_f32_16x16x32_bf16 v[20:23], v[200:203], v[232:235], v[20:23]
	v_mfma_f32_16x16x32_bf16 v[16:19], v[208:211], v[232:235], v[16:19]
	v_mfma_f32_16x16x32_bf16 v[4:7], v[200:203], v[240:243], v[4:7]
	v_mfma_f32_16x16x32_bf16 v[0:3], v[208:211], v[240:243], v[0:3]
	v_mfma_f32_16x16x32_bf16 v[52:55], v[204:207], v[220:223], v[52:55]
	v_mfma_f32_16x16x32_bf16 v[48:51], v[212:215], v[220:223], v[48:51]
	v_mfma_f32_16x16x32_bf16 v[36:39], v[204:207], v[228:231], v[36:39]
	v_mfma_f32_16x16x32_bf16 v[32:35], v[212:215], v[228:231], v[32:35]
	v_mfma_f32_16x16x32_bf16 v[20:23], v[204:207], v[236:239], v[20:23]
	v_mfma_f32_16x16x32_bf16 v[16:19], v[212:215], v[236:239], v[16:19]
	v_mfma_f32_16x16x32_bf16 v[4:7], v[204:207], v[244:247], v[4:7]
	v_mfma_f32_16x16x32_bf16 v[0:3], v[212:215], v[244:247], v[0:3]
	s_setprio 0
	s_barrier
	s_add_i32 s67, s67, 2
	s_add_u32 s28, s28, 0x100
	s_addc_u32 s29, s29, 0
	s_add_u32 s63, s63, 0x100
	s_addc_u32 s66, s66, 0
	s_cmp_gt_u32 s67, 13
	s_cbranch_scc0 .LBB0_568
	v_lshl_add_u32 v142, s51, 8, v144
	v_lshl_or_b32 v140, s1, 8, v146
	v_ashrrev_i32_e32 v143, 31, v142
	v_ashrrev_i32_e32 v141, 31, v140
	v_lshlrev_b64 v[138:139], 10, v[142:143]
	v_lshl_add_u64 v[138:139], v[138:139], 0, v[140:141]
	v_lshlrev_b64 v[156:157], 2, v[138:139]
	v_lshl_add_u64 v[158:159], s[16:17], 0, v[156:157]
	v_mov_b32_e32 v248, v158
	v_mov_b32_e32 v249, v159
	global_load_dwordx4 v[200:203], v[248:249], off
	global_load_dwordx4 v[204:207], v[248:249], off offset:16
	global_load_dwordx4 v[208:211], v[248:249], off offset:512
	global_load_dwordx4 v[212:215], v[248:249], off offset:528
	s_mov_b64 s[98:99], 0x10000
	v_lshl_add_u64 v[250:251], v[248:249], 0, s[98:99]
	global_load_dwordx4 v[216:219], v[250:251], off
	global_load_dwordx4 v[220:223], v[250:251], off offset:16
	global_load_dwordx4 v[224:227], v[250:251], off offset:512
	global_load_dwordx4 v[228:231], v[250:251], off offset:528
	s_mov_b64 s[98:99], 0x20000
	v_lshl_add_u64 v[250:251], v[248:249], 0, s[98:99]
	global_load_dwordx4 v[232:235], v[250:251], off
	global_load_dwordx4 v[236:239], v[250:251], off offset:16
	global_load_dwordx4 v[240:243], v[250:251], off offset:512
	global_load_dwordx4 v[244:247], v[250:251], off offset:528
	s_waitcnt vmcnt(8)
	s_nop 1
	v_mov_b32_e32 v148, v204
	v_mov_b32_e32 v149, v205
	v_mov_b32_e32 v150, v206
	v_mov_b32_e32 v151, v207
	s_nop 1
	v_mov_b32_e32 v152, v200
	v_mov_b32_e32 v153, v201
	v_mov_b32_e32 v154, v202
	v_mov_b32_e32 v155, v203
	v_pk_add_f32 v[122:123], v[122:123], v[150:151]
	v_pk_add_f32 v[126:127], v[126:127], v[154:155]
	v_pk_add_f32 v[124:125], v[124:125], v[152:153]
	v_lshl_add_u64 v[152:153], s[12:13], 0, v[156:157]
	v_pk_add_f32 v[120:121], v[120:121], v[148:149]
	global_store_dwordx4 v[152:153], v[124:127], off
	global_store_dwordx4 v[152:153], v[120:123], off offset:16
	v_cvt_pk_bf16_f32 v148, v124, v125
	v_mul_f32_e32 v125, v125, v125
	v_fmac_f32_e32 v125, v124, v124
	v_mul_f32_e32 v124, v127, v127
	v_cvt_pk_bf16_f32 v150, v120, v121
	v_fmac_f32_e32 v124, v126, v126
	v_mul_f32_e32 v121, v121, v121
	v_add_f32_e32 v124, v125, v124
	v_fmac_f32_e32 v121, v120, v120
	v_cvt_pk_bf16_f32 v149, v126, v127
	v_cvt_pk_bf16_f32 v151, v122, v123
	v_lshl_add_u64 v[154:155], v[138:139], 1, s[18:19]
	v_add_f32_e32 v120, v124, v121
	v_mul_f32_e32 v121, v123, v123
	global_store_dwordx4 v[154:155], v[148:151], off
	v_fmac_f32_e32 v121, v122, v122
	s_nop 0
	v_add_f32_e32 v148, v121, v120
	s_nop 1
	v_mov_b32_e32 v120, v212
	v_mov_b32_e32 v121, v213
	v_mov_b32_e32 v122, v214
	v_mov_b32_e32 v123, v215
	s_nop 1
	v_mov_b32_e32 v124, v208
	v_mov_b32_e32 v125, v209
	v_mov_b32_e32 v126, v210
	v_mov_b32_e32 v127, v211
	v_pk_add_f32 v[114:115], v[114:115], v[122:123]
	v_pk_add_f32 v[118:119], v[118:119], v[126:127]
	v_pk_add_f32 v[116:117], v[116:117], v[124:125]
	v_pk_add_f32 v[112:113], v[112:113], v[120:121]
	global_store_dwordx4 v[152:153], v[116:119], off offset:512
	global_store_dwordx4 v[152:153], v[112:115], off offset:528
	v_cvt_pk_bf16_f32 v123, v114, v115
	v_cvt_pk_bf16_f32 v120, v116, v117
	v_mul_f32_e32 v115, v115, v115
	v_fmac_f32_e32 v115, v114, v114
	v_mul_f32_e32 v114, v117, v117
	v_fmac_f32_e32 v114, v116, v116
	v_mul_f32_e32 v116, v119, v119
	v_cvt_pk_bf16_f32 v122, v112, v113
	v_fmac_f32_e32 v116, v118, v118
	v_mul_f32_e32 v113, v113, v113
	v_add_f32_e32 v114, v114, v116
	v_fmac_f32_e32 v113, v112, v112
	v_add_f32_e32 v112, v114, v113
	v_add_f32_e32 v112, v115, v112
	v_add_f32_e32 v112, v148, v112
	ds_bpermute_b32 v113, v180, v112
	v_cvt_pk_bf16_f32 v121, v118, v119
	global_store_dwordx4 v[154:155], v[120:123], off offset:256
	s_waitcnt lgkmcnt(0)
	v_add_f32_e32 v114, v112, v113
	ds_bpermute_b32 v115, v181, v114
	v_lshl_add_u64 v[112:113], v[142:143], 3, s[14:15]
	s_and_saveexec_b64 s[28:29], s[8:9]
	s_cbranch_execz .LBB0_571
	s_waitcnt lgkmcnt(0)
	v_add_f32_e32 v114, v114, v115
	v_fma_f32 v114, v114, s65, 0.5
	v_trunc_f32_e32 v114, v114
	v_mul_f32_e32 v115, 0x2f800000, v114
	v_floor_f32_e32 v115, v115
	v_fmac_f32_e32 v114, 0xcf800000, v115
	v_cvt_u32_f32_e32 v114, v114
	v_cvt_u32_f32_e32 v115, v115
	global_atomic_add_x2 v[112:113], v[114:115], off
.LBB0_571:
	s_or_b64 exec, exec, s[28:29]
	v_or_b32_e32 v114, 16, v142
	s_waitcnt lgkmcnt(0)
	v_ashrrev_i32_e32 v115, 31, v114
	v_lshlrev_b64 v[114:115], 10, v[114:115]
	v_lshl_add_u64 v[122:123], v[114:115], 0, v[140:141]
	v_lshlrev_b64 v[124:125], 2, v[122:123]
	v_lshl_add_u64 v[126:127], s[16:17], 0, v[124:125]
	s_mov_b64 s[98:99], 0x30000
	v_lshl_add_u64 v[250:251], v[248:249], 0, s[98:99]
	global_load_dwordx4 v[200:203], v[250:251], off
	global_load_dwordx4 v[204:207], v[250:251], off offset:16
	global_load_dwordx4 v[208:211], v[250:251], off offset:512
	global_load_dwordx4 v[212:215], v[250:251], off offset:528
	s_waitcnt vmcnt(12)
	s_nop 1
	v_mov_b32_e32 v114, v216
	v_mov_b32_e32 v115, v217
	v_mov_b32_e32 v116, v218
	v_mov_b32_e32 v117, v219
	s_nop 1
	v_mov_b32_e32 v118, v220
	v_mov_b32_e32 v119, v221
	v_mov_b32_e32 v120, v222
	v_mov_b32_e32 v121, v223
	v_lshl_add_u64 v[122:123], v[122:123], 1, s[18:19]
	v_lshl_add_u64 v[124:125], s[12:13], 0, v[124:125]
	v_pk_add_f32 v[110:111], v[110:111], v[116:117]
	v_pk_add_f32 v[108:109], v[108:109], v[114:115]
	v_pk_add_f32 v[106:107], v[106:107], v[120:121]
	v_pk_add_f32 v[104:105], v[104:105], v[118:119]
	v_cvt_pk_bf16_f32 v114, v108, v109
	v_cvt_pk_bf16_f32 v115, v110, v111
	v_cvt_pk_bf16_f32 v116, v104, v105
	v_cvt_pk_bf16_f32 v117, v106, v107
	global_store_dwordx4 v[124:125], v[108:111], off
	global_store_dwordx4 v[124:125], v[104:107], off offset:16
	global_store_dwordx4 v[122:123], v[114:117], off
	s_nop 1
	v_mov_b32_e32 v114, v224
	v_mov_b32_e32 v115, v225
	v_mov_b32_e32 v116, v226
	v_mov_b32_e32 v117, v227
	s_nop 0
	s_nop 1
	v_mov_b32_e32 v118, v228
	v_mov_b32_e32 v119, v229
	v_mov_b32_e32 v120, v230
	v_mov_b32_e32 v121, v231
	v_mul_f32_e32 v109, v109, v109
	v_mul_f32_e32 v111, v111, v111
	v_mul_f32_e32 v105, v105, v105
	v_fmac_f32_e32 v109, v108, v108
	v_fmac_f32_e32 v111, v110, v110
	v_mul_f32_e32 v107, v107, v107
	v_fmac_f32_e32 v105, v104, v104
	v_add_f32_e32 v104, v109, v111
	v_fmac_f32_e32 v107, v106, v106
	v_add_f32_e32 v104, v104, v105
	v_add_f32_e32 v108, v107, v104
	v_pk_add_f32 v[102:103], v[102:103], v[116:117]
	v_pk_add_f32 v[100:101], v[100:101], v[114:115]
	v_pk_add_f32 v[106:107], v[98:99], v[120:121]
	v_pk_add_f32 v[104:105], v[96:97], v[118:119]
	v_mul_f32_e32 v97, v101, v101
	v_mul_f32_e32 v98, v103, v103
	v_mul_f32_e32 v99, v105, v105
	v_fmac_f32_e32 v97, v100, v100
	v_fmac_f32_e32 v98, v102, v102
	v_mul_f32_e32 v96, v107, v107
	v_add_f32_e32 v97, v97, v98
	v_fmac_f32_e32 v99, v104, v104
	v_fmac_f32_e32 v96, v106, v106
	v_add_f32_e32 v97, v97, v99
	v_add_f32_e32 v96, v96, v97
	v_add_f32_e32 v96, v108, v96
	ds_bpermute_b32 v97, v180, v96
	global_store_dwordx4 v[124:125], v[100:103], off offset:512
	global_store_dwordx4 v[124:125], v[104:107], off offset:528
	v_cvt_pk_bf16_f32 v98, v100, v101
	v_cvt_pk_bf16_f32 v99, v102, v103
	v_cvt_pk_bf16_f32 v100, v104, v105
	s_waitcnt lgkmcnt(0)
	v_add_f32_e32 v96, v96, v97
	ds_bpermute_b32 v97, v181, v96
	v_cvt_pk_bf16_f32 v101, v106, v107
	global_store_dwordx4 v[122:123], v[98:101], off offset:256
	s_and_saveexec_b64 s[28:29], s[8:9]
	v_readlane_b32 s62, v254, 61
	v_readlane_b32 s66, v254, 63
	v_readlane_b32 s38, v254, 59
	v_readlane_b32 s63, v254, 62
	v_readlane_b32 s67, v255, 0
	v_readlane_b32 s39, v254, 60
	s_cbranch_execz .LBB0_573
	s_waitcnt lgkmcnt(0)
	v_add_f32_e32 v96, v96, v97
	v_fma_f32 v96, v96, s65, 0.5
	v_trunc_f32_e32 v96, v96
	v_mul_f32_e32 v97, 0x2f800000, v96
	v_floor_f32_e32 v97, v97
	v_fmac_f32_e32 v96, 0xcf800000, v97
	v_cvt_u32_f32_e32 v96, v96
	v_cvt_u32_f32_e32 v97, v97
	global_atomic_add_x2 v[112:113], v[96:97], off offset:128
.LBB0_573:
	s_or_b64 exec, exec, s[28:29]
	v_or_b32_e32 v96, 32, v142
	s_waitcnt lgkmcnt(0)
	v_ashrrev_i32_e32 v97, 31, v96
	v_lshlrev_b64 v[96:97], 10, v[96:97]
	v_lshl_add_u64 v[104:105], v[96:97], 0, v[140:141]
	v_lshlrev_b64 v[106:107], 2, v[104:105]
	v_lshl_add_u64 v[108:109], s[16:17], 0, v[106:107]
	s_mov_b64 s[98:99], 0x80000
	v_lshl_add_u64 v[250:251], v[248:249], 0, s[98:99]
	global_load_dwordx4 v[216:219], v[250:251], off
	global_load_dwordx4 v[220:223], v[250:251], off offset:16
	global_load_dwordx4 v[224:227], v[250:251], off offset:512
	global_load_dwordx4 v[228:231], v[250:251], off offset:528
	s_waitcnt vmcnt(16)
	s_nop 1
	v_mov_b32_e32 v96, v232
	v_mov_b32_e32 v97, v233
	v_mov_b32_e32 v98, v234
	v_mov_b32_e32 v99, v235
	s_nop 1
	v_mov_b32_e32 v100, v236
	v_mov_b32_e32 v101, v237
	v_mov_b32_e32 v102, v238
	v_mov_b32_e32 v103, v239
	v_lshl_add_u64 v[104:105], v[104:105], 1, s[18:19]
	v_lshl_add_u64 v[106:107], s[12:13], 0, v[106:107]
	v_pk_add_f32 v[94:95], v[94:95], v[98:99]
	v_pk_add_f32 v[92:93], v[92:93], v[96:97]
	v_pk_add_f32 v[90:91], v[90:91], v[102:103]
	v_pk_add_f32 v[88:89], v[88:89], v[100:101]
	v_cvt_pk_bf16_f32 v96, v92, v93
	v_cvt_pk_bf16_f32 v97, v94, v95
	v_cvt_pk_bf16_f32 v98, v88, v89
	v_cvt_pk_bf16_f32 v99, v90, v91
	global_store_dwordx4 v[106:107], v[92:95], off
	global_store_dwordx4 v[106:107], v[88:91], off offset:16
	global_store_dwordx4 v[104:105], v[96:99], off
	s_nop 1
	v_mov_b32_e32 v96, v240
	v_mov_b32_e32 v97, v241
	v_mov_b32_e32 v98, v242
	v_mov_b32_e32 v99, v243
	s_nop 0
	s_nop 1
	v_mov_b32_e32 v100, v244
	v_mov_b32_e32 v101, v245
	v_mov_b32_e32 v102, v246
	v_mov_b32_e32 v103, v247
	v_mul_f32_e32 v93, v93, v93
	v_mul_f32_e32 v95, v95, v95
	v_mul_f32_e32 v89, v89, v89
	v_fmac_f32_e32 v93, v92, v92
	v_fmac_f32_e32 v95, v94, v94
	v_mul_f32_e32 v91, v91, v91
	v_fmac_f32_e32 v89, v88, v88
	v_add_f32_e32 v88, v93, v95
	v_fmac_f32_e32 v91, v90, v90
	v_add_f32_e32 v88, v88, v89
	v_add_f32_e32 v92, v91, v88
	v_pk_add_f32 v[86:87], v[86:87], v[98:99]
	v_pk_add_f32 v[84:85], v[84:85], v[96:97]
	v_pk_add_f32 v[90:91], v[82:83], v[102:103]
	v_pk_add_f32 v[88:89], v[80:81], v[100:101]
	v_mul_f32_e32 v81, v85, v85
	v_mul_f32_e32 v82, v87, v87
	v_mul_f32_e32 v83, v89, v89
	v_fmac_f32_e32 v81, v84, v84
	v_fmac_f32_e32 v82, v86, v86
	v_mul_f32_e32 v80, v91, v91
	v_add_f32_e32 v81, v81, v82
	v_fmac_f32_e32 v83, v88, v88
	v_fmac_f32_e32 v80, v90, v90
	v_add_f32_e32 v81, v81, v83
	v_add_f32_e32 v80, v80, v81
	v_add_f32_e32 v80, v92, v80
	ds_bpermute_b32 v81, v180, v80
	global_store_dwordx4 v[106:107], v[84:87], off offset:512
	global_store_dwordx4 v[106:107], v[88:91], off offset:528
	v_cvt_pk_bf16_f32 v82, v84, v85
	v_cvt_pk_bf16_f32 v83, v86, v87
	v_cvt_pk_bf16_f32 v84, v88, v89
	s_waitcnt lgkmcnt(0)
	v_add_f32_e32 v80, v80, v81
	ds_bpermute_b32 v81, v181, v80
	v_cvt_pk_bf16_f32 v85, v90, v91
	global_store_dwordx4 v[104:105], v[82:85], off offset:256
	s_and_saveexec_b64 s[28:29], s[8:9]
	s_cbranch_execz .LBB0_575
	s_waitcnt lgkmcnt(0)
	v_add_f32_e32 v80, v80, v81
	v_fma_f32 v80, v80, s65, 0.5
	v_trunc_f32_e32 v80, v80
	v_mul_f32_e32 v81, 0x2f800000, v80
	v_floor_f32_e32 v81, v81
	v_fmac_f32_e32 v80, 0xcf800000, v81
	v_cvt_u32_f32_e32 v80, v80
	v_cvt_u32_f32_e32 v81, v81
	global_atomic_add_x2 v[112:113], v[80:81], off offset:256
.LBB0_575:
	s_or_b64 exec, exec, s[28:29]
	v_or_b32_e32 v80, 48, v142
	s_waitcnt lgkmcnt(0)
	v_ashrrev_i32_e32 v81, 31, v80
	v_lshlrev_b64 v[80:81], 10, v[80:81]
	v_lshl_add_u64 v[88:89], v[80:81], 0, v[140:141]
	v_lshlrev_b64 v[90:91], 2, v[88:89]
	v_lshl_add_u64 v[92:93], s[16:17], 0, v[90:91]
	s_mov_b64 s[98:99], 0x90000
	v_lshl_add_u64 v[250:251], v[248:249], 0, s[98:99]
	global_load_dwordx4 v[232:235], v[250:251], off
	global_load_dwordx4 v[236:239], v[250:251], off offset:16
	global_load_dwordx4 v[240:243], v[250:251], off offset:512
	global_load_dwordx4 v[244:247], v[250:251], off offset:528
	s_waitcnt vmcnt(16)
	s_nop 1
	v_mov_b32_e32 v80, v200
	v_mov_b32_e32 v81, v201
	v_mov_b32_e32 v82, v202
	v_mov_b32_e32 v83, v203
	s_nop 1
	v_mov_b32_e32 v84, v204
	v_mov_b32_e32 v85, v205
	v_mov_b32_e32 v86, v206
	v_mov_b32_e32 v87, v207
	v_lshl_add_u64 v[88:89], v[88:89], 1, s[18:19]
	v_lshl_add_u64 v[90:91], s[12:13], 0, v[90:91]
	v_pk_add_f32 v[78:79], v[78:79], v[82:83]
	v_pk_add_f32 v[76:77], v[76:77], v[80:81]
	v_pk_add_f32 v[74:75], v[74:75], v[86:87]
	v_pk_add_f32 v[72:73], v[72:73], v[84:85]
	v_cvt_pk_bf16_f32 v80, v76, v77
	v_cvt_pk_bf16_f32 v81, v78, v79
	v_cvt_pk_bf16_f32 v82, v72, v73
	v_cvt_pk_bf16_f32 v83, v74, v75
	global_store_dwordx4 v[90:91], v[76:79], off
	global_store_dwordx4 v[90:91], v[72:75], off offset:16
	global_store_dwordx4 v[88:89], v[80:83], off
	s_nop 1
	v_mov_b32_e32 v80, v208
	v_mov_b32_e32 v81, v209
	v_mov_b32_e32 v82, v210
	v_mov_b32_e32 v83, v211
	s_nop 0
	s_nop 1
	v_mov_b32_e32 v84, v212
	v_mov_b32_e32 v85, v213
	v_mov_b32_e32 v86, v214
	v_mov_b32_e32 v87, v215
	v_mul_f32_e32 v77, v77, v77
	v_mul_f32_e32 v79, v79, v79
	v_mul_f32_e32 v73, v73, v73
	v_fmac_f32_e32 v77, v76, v76
	v_fmac_f32_e32 v79, v78, v78
	v_mul_f32_e32 v75, v75, v75
	v_fmac_f32_e32 v73, v72, v72
	v_add_f32_e32 v72, v77, v79
	v_fmac_f32_e32 v75, v74, v74
	v_add_f32_e32 v72, v72, v73
	v_add_f32_e32 v76, v75, v72
	v_pk_add_f32 v[70:71], v[70:71], v[82:83]
	v_pk_add_f32 v[68:69], v[68:69], v[80:81]
	v_pk_add_f32 v[74:75], v[66:67], v[86:87]
	v_pk_add_f32 v[72:73], v[64:65], v[84:85]
	v_mul_f32_e32 v65, v69, v69
	v_mul_f32_e32 v66, v71, v71
	v_mul_f32_e32 v67, v73, v73
	v_fmac_f32_e32 v65, v68, v68
	v_fmac_f32_e32 v66, v70, v70
	v_mul_f32_e32 v64, v75, v75
	v_add_f32_e32 v65, v65, v66
	v_fmac_f32_e32 v67, v72, v72
	v_fmac_f32_e32 v64, v74, v74
	v_add_f32_e32 v65, v65, v67
	v_add_f32_e32 v64, v64, v65
	v_add_f32_e32 v64, v76, v64
	ds_bpermute_b32 v65, v180, v64
	global_store_dwordx4 v[90:91], v[68:71], off offset:512
	global_store_dwordx4 v[90:91], v[72:75], off offset:528
	v_cvt_pk_bf16_f32 v66, v68, v69
	v_cvt_pk_bf16_f32 v67, v70, v71
	v_cvt_pk_bf16_f32 v68, v72, v73
	s_waitcnt lgkmcnt(0)
	v_add_f32_e32 v64, v64, v65
	ds_bpermute_b32 v65, v181, v64
	v_cvt_pk_bf16_f32 v69, v74, v75
	global_store_dwordx4 v[88:89], v[66:69], off offset:256
	s_and_saveexec_b64 s[28:29], s[8:9]
	s_cbranch_execz .LBB0_577
	s_waitcnt lgkmcnt(0)
	v_add_f32_e32 v64, v64, v65
	v_fma_f32 v64, v64, s65, 0.5
	v_trunc_f32_e32 v64, v64
	v_mul_f32_e32 v65, 0x2f800000, v64
	v_floor_f32_e32 v65, v65
	v_fmac_f32_e32 v64, 0xcf800000, v65
	v_cvt_u32_f32_e32 v64, v64
	v_cvt_u32_f32_e32 v65, v65
	global_atomic_add_x2 v[112:113], v[64:65], off offset:384
.LBB0_577:
	s_or_b64 exec, exec, s[28:29]
	s_mov_b64 s[28:29], 0x20000
	v_lshl_add_u64 v[72:73], v[138:139], 0, s[28:29]
	v_lshlrev_b64 v[74:75], 2, v[72:73]
	v_lshl_add_u64 v[76:77], s[16:17], 0, v[74:75]
	s_waitcnt lgkmcnt(0)
	s_mov_b64 s[98:99], 0xa0000
	v_lshl_add_u64 v[250:251], v[248:249], 0, s[98:99]
	global_load_dwordx4 v[200:203], v[250:251], off
	global_load_dwordx4 v[204:207], v[250:251], off offset:16
	global_load_dwordx4 v[208:211], v[250:251], off offset:512
	global_load_dwordx4 v[212:215], v[250:251], off offset:528
	s_waitcnt vmcnt(16)
	s_nop 1
	v_mov_b32_e32 v64, v216
	v_mov_b32_e32 v65, v217
	v_mov_b32_e32 v66, v218
	v_mov_b32_e32 v67, v219
	s_nop 1
	v_mov_b32_e32 v68, v220
	v_mov_b32_e32 v69, v221
	v_mov_b32_e32 v70, v222
	v_mov_b32_e32 v71, v223
	v_lshl_add_u64 v[72:73], v[72:73], 1, s[18:19]
	v_lshl_add_u64 v[74:75], s[12:13], 0, v[74:75]
	v_pk_add_f32 v[62:63], v[62:63], v[66:67]
	v_pk_add_f32 v[60:61], v[60:61], v[64:65]
	v_pk_add_f32 v[58:59], v[58:59], v[70:71]
	v_pk_add_f32 v[56:57], v[56:57], v[68:69]
	v_cvt_pk_bf16_f32 v64, v60, v61
	v_cvt_pk_bf16_f32 v65, v62, v63
	v_cvt_pk_bf16_f32 v66, v56, v57
	v_cvt_pk_bf16_f32 v67, v58, v59
	global_store_dwordx4 v[74:75], v[60:63], off
	global_store_dwordx4 v[74:75], v[56:59], off offset:16
	global_store_dwordx4 v[72:73], v[64:67], off
	s_nop 1
	v_mov_b32_e32 v64, v224
	v_mov_b32_e32 v65, v225
	v_mov_b32_e32 v66, v226
	v_mov_b32_e32 v67, v227
	s_nop 0
	s_nop 1
	v_mov_b32_e32 v68, v228
	v_mov_b32_e32 v69, v229
	v_mov_b32_e32 v70, v230
	v_mov_b32_e32 v71, v231
	v_mul_f32_e32 v61, v61, v61
	v_mul_f32_e32 v63, v63, v63
	v_mul_f32_e32 v57, v57, v57
	v_fmac_f32_e32 v61, v60, v60
	v_fmac_f32_e32 v63, v62, v62
	v_mul_f32_e32 v59, v59, v59
	v_fmac_f32_e32 v57, v56, v56
	v_add_f32_e32 v56, v61, v63
	v_fmac_f32_e32 v59, v58, v58
	v_add_f32_e32 v56, v56, v57
	v_add_f32_e32 v60, v59, v56
	v_pk_add_f32 v[54:55], v[54:55], v[66:67]
	v_pk_add_f32 v[52:53], v[52:53], v[64:65]
	v_pk_add_f32 v[58:59], v[50:51], v[70:71]
	v_pk_add_f32 v[56:57], v[48:49], v[68:69]
	v_mul_f32_e32 v49, v53, v53
	v_mul_f32_e32 v50, v55, v55
	v_mul_f32_e32 v51, v57, v57
	v_fmac_f32_e32 v49, v52, v52
	v_fmac_f32_e32 v50, v54, v54
	v_mul_f32_e32 v48, v59, v59
	v_add_f32_e32 v49, v49, v50
	v_fmac_f32_e32 v51, v56, v56
	v_fmac_f32_e32 v48, v58, v58
	v_add_f32_e32 v49, v49, v51
	v_add_f32_e32 v48, v48, v49
	v_add_f32_e32 v48, v60, v48
	ds_bpermute_b32 v49, v180, v48
	global_store_dwordx4 v[74:75], v[52:55], off offset:512
	global_store_dwordx4 v[74:75], v[56:59], off offset:528
	v_cvt_pk_bf16_f32 v50, v52, v53
	v_cvt_pk_bf16_f32 v51, v54, v55
	v_cvt_pk_bf16_f32 v52, v56, v57
	s_waitcnt lgkmcnt(0)
	v_add_f32_e32 v48, v48, v49
	ds_bpermute_b32 v49, v181, v48
	v_cvt_pk_bf16_f32 v53, v58, v59
	global_store_dwordx4 v[72:73], v[50:53], off offset:256
	s_and_saveexec_b64 s[28:29], s[8:9]
	s_cbranch_execz .LBB0_579
	s_waitcnt lgkmcnt(0)
	v_add_f32_e32 v48, v48, v49
	v_fma_f32 v48, v48, s65, 0.5
	v_trunc_f32_e32 v48, v48
	v_mul_f32_e32 v49, 0x2f800000, v48
	v_floor_f32_e32 v49, v49
	v_fmac_f32_e32 v48, 0xcf800000, v49
	v_cvt_u32_f32_e32 v48, v48
	v_cvt_u32_f32_e32 v49, v49
	global_atomic_add_x2 v[112:113], v[48:49], off offset:1024
.LBB0_579:
	s_or_b64 exec, exec, s[28:29]
	s_mov_b64 s[28:29], 0x24000
	v_lshl_add_u64 v[56:57], v[138:139], 0, s[28:29]
	v_lshlrev_b64 v[58:59], 2, v[56:57]
	v_lshl_add_u64 v[60:61], s[16:17], 0, v[58:59]
	s_waitcnt lgkmcnt(0)
	s_mov_b64 s[98:99], 0xb0000
	v_lshl_add_u64 v[250:251], v[248:249], 0, s[98:99]
	global_load_dwordx4 v[216:219], v[250:251], off
	global_load_dwordx4 v[220:223], v[250:251], off offset:16
	global_load_dwordx4 v[224:227], v[250:251], off offset:512
	global_load_dwordx4 v[228:231], v[250:251], off offset:528
	s_waitcnt vmcnt(16)
	s_nop 1
	v_mov_b32_e32 v48, v232
	v_mov_b32_e32 v49, v233
	v_mov_b32_e32 v50, v234
	v_mov_b32_e32 v51, v235
	s_nop 1
	v_mov_b32_e32 v52, v236
	v_mov_b32_e32 v53, v237
	v_mov_b32_e32 v54, v238
	v_mov_b32_e32 v55, v239
	v_lshl_add_u64 v[56:57], v[56:57], 1, s[18:19]
	v_lshl_add_u64 v[58:59], s[12:13], 0, v[58:59]
	v_pk_add_f32 v[46:47], v[46:47], v[50:51]
	v_pk_add_f32 v[44:45], v[44:45], v[48:49]
	v_pk_add_f32 v[42:43], v[42:43], v[54:55]
	v_pk_add_f32 v[40:41], v[40:41], v[52:53]
	v_cvt_pk_bf16_f32 v48, v44, v45
	v_cvt_pk_bf16_f32 v49, v46, v47
	v_cvt_pk_bf16_f32 v50, v40, v41
	v_cvt_pk_bf16_f32 v51, v42, v43
	global_store_dwordx4 v[58:59], v[44:47], off
	global_store_dwordx4 v[58:59], v[40:43], off offset:16
	global_store_dwordx4 v[56:57], v[48:51], off
	s_nop 1
	v_mov_b32_e32 v48, v240
	v_mov_b32_e32 v49, v241
	v_mov_b32_e32 v50, v242
	v_mov_b32_e32 v51, v243
	s_nop 0
	s_nop 1
	v_mov_b32_e32 v52, v244
	v_mov_b32_e32 v53, v245
	v_mov_b32_e32 v54, v246
	v_mov_b32_e32 v55, v247
	v_mul_f32_e32 v45, v45, v45
	v_mul_f32_e32 v47, v47, v47
	v_mul_f32_e32 v41, v41, v41
	v_fmac_f32_e32 v45, v44, v44
	v_fmac_f32_e32 v47, v46, v46
	v_mul_f32_e32 v43, v43, v43
	v_fmac_f32_e32 v41, v40, v40
	v_add_f32_e32 v40, v45, v47
	v_fmac_f32_e32 v43, v42, v42
	v_add_f32_e32 v40, v40, v41
	v_add_f32_e32 v44, v43, v40
	v_pk_add_f32 v[38:39], v[38:39], v[50:51]
	v_pk_add_f32 v[36:37], v[36:37], v[48:49]
	v_pk_add_f32 v[42:43], v[34:35], v[54:55]
	v_pk_add_f32 v[40:41], v[32:33], v[52:53]
	v_mul_f32_e32 v33, v37, v37
	v_mul_f32_e32 v34, v39, v39
	v_mul_f32_e32 v35, v41, v41
	v_fmac_f32_e32 v33, v36, v36
	v_fmac_f32_e32 v34, v38, v38
	v_mul_f32_e32 v32, v43, v43
	v_add_f32_e32 v33, v33, v34
	v_fmac_f32_e32 v35, v40, v40
	v_fmac_f32_e32 v32, v42, v42
	v_add_f32_e32 v33, v33, v35
	v_add_f32_e32 v32, v32, v33
	v_add_f32_e32 v32, v44, v32
	ds_bpermute_b32 v33, v180, v32
	global_store_dwordx4 v[58:59], v[36:39], off offset:512
	global_store_dwordx4 v[58:59], v[40:43], off offset:528
	v_cvt_pk_bf16_f32 v34, v36, v37
	v_cvt_pk_bf16_f32 v35, v38, v39
	v_cvt_pk_bf16_f32 v36, v40, v41
	s_waitcnt lgkmcnt(0)
	v_add_f32_e32 v32, v32, v33
	ds_bpermute_b32 v33, v181, v32
	v_cvt_pk_bf16_f32 v37, v42, v43
	global_store_dwordx4 v[56:57], v[34:37], off offset:256
	s_and_saveexec_b64 s[28:29], s[8:9]
	s_cbranch_execz .LBB0_581
	s_waitcnt lgkmcnt(0)
	v_add_f32_e32 v32, v32, v33
	v_fma_f32 v32, v32, s65, 0.5
	v_trunc_f32_e32 v32, v32
	v_mul_f32_e32 v33, 0x2f800000, v32
	v_floor_f32_e32 v33, v33
	v_fmac_f32_e32 v32, 0xcf800000, v33
	v_cvt_u32_f32_e32 v32, v32
	v_cvt_u32_f32_e32 v33, v33
	global_atomic_add_x2 v[112:113], v[32:33], off offset:1152
.LBB0_581:
	s_or_b64 exec, exec, s[28:29]
	s_mov_b64 s[28:29], 0x28000
	v_lshl_add_u64 v[40:41], v[138:139], 0, s[28:29]
	v_lshlrev_b64 v[42:43], 2, v[40:41]
	v_lshl_add_u64 v[44:45], s[16:17], 0, v[42:43]
	s_waitcnt lgkmcnt(0)
	s_waitcnt vmcnt(12)
	s_nop 1
	v_mov_b32_e32 v32, v200
	v_mov_b32_e32 v33, v201
	v_mov_b32_e32 v34, v202
	v_mov_b32_e32 v35, v203
	s_nop 1
	v_mov_b32_e32 v36, v204
	v_mov_b32_e32 v37, v205
	v_mov_b32_e32 v38, v206
	v_mov_b32_e32 v39, v207
	v_lshl_add_u64 v[40:41], v[40:41], 1, s[18:19]
	v_lshl_add_u64 v[42:43], s[12:13], 0, v[42:43]
	v_pk_add_f32 v[30:31], v[30:31], v[34:35]
	v_pk_add_f32 v[28:29], v[28:29], v[32:33]
	v_pk_add_f32 v[26:27], v[26:27], v[38:39]
	v_pk_add_f32 v[24:25], v[24:25], v[36:37]
	v_cvt_pk_bf16_f32 v32, v28, v29
	v_cvt_pk_bf16_f32 v33, v30, v31
	v_cvt_pk_bf16_f32 v34, v24, v25
	v_cvt_pk_bf16_f32 v35, v26, v27
	global_store_dwordx4 v[42:43], v[28:31], off
	global_store_dwordx4 v[42:43], v[24:27], off offset:16
	global_store_dwordx4 v[40:41], v[32:35], off
	s_nop 1
	v_mov_b32_e32 v32, v208
	v_mov_b32_e32 v33, v209
	v_mov_b32_e32 v34, v210
	v_mov_b32_e32 v35, v211
	s_nop 0
	s_nop 1
	v_mov_b32_e32 v36, v212
	v_mov_b32_e32 v37, v213
	v_mov_b32_e32 v38, v214
	v_mov_b32_e32 v39, v215
	v_mul_f32_e32 v29, v29, v29
	v_mul_f32_e32 v31, v31, v31
	v_mul_f32_e32 v25, v25, v25
	v_fmac_f32_e32 v29, v28, v28
	v_fmac_f32_e32 v31, v30, v30
	v_mul_f32_e32 v27, v27, v27
	v_fmac_f32_e32 v25, v24, v24
	v_add_f32_e32 v24, v29, v31
	v_fmac_f32_e32 v27, v26, v26
	v_add_f32_e32 v24, v24, v25
	v_add_f32_e32 v28, v27, v24
	v_pk_add_f32 v[22:23], v[22:23], v[34:35]
	v_pk_add_f32 v[20:21], v[20:21], v[32:33]
	v_pk_add_f32 v[26:27], v[18:19], v[38:39]
	v_pk_add_f32 v[24:25], v[16:17], v[36:37]
	v_mul_f32_e32 v17, v21, v21
	v_mul_f32_e32 v18, v23, v23
	v_mul_f32_e32 v19, v25, v25
	v_fmac_f32_e32 v17, v20, v20
	v_fmac_f32_e32 v18, v22, v22
	v_mul_f32_e32 v16, v27, v27
	v_add_f32_e32 v17, v17, v18
	v_fmac_f32_e32 v19, v24, v24
	v_fmac_f32_e32 v16, v26, v26
	v_add_f32_e32 v17, v17, v19
	v_add_f32_e32 v16, v16, v17
	v_add_f32_e32 v16, v28, v16
	ds_bpermute_b32 v17, v180, v16
	global_store_dwordx4 v[42:43], v[20:23], off offset:512
	global_store_dwordx4 v[42:43], v[24:27], off offset:528
	v_cvt_pk_bf16_f32 v18, v20, v21
	v_cvt_pk_bf16_f32 v19, v22, v23
	v_cvt_pk_bf16_f32 v20, v24, v25
	s_waitcnt lgkmcnt(0)
	v_add_f32_e32 v16, v16, v17
	ds_bpermute_b32 v17, v181, v16
	v_cvt_pk_bf16_f32 v21, v26, v27
	global_store_dwordx4 v[40:41], v[18:21], off offset:256
	s_and_saveexec_b64 s[28:29], s[8:9]
	s_cbranch_execz .LBB0_583
	s_waitcnt lgkmcnt(0)
	v_add_f32_e32 v16, v16, v17
	v_fma_f32 v16, v16, s65, 0.5
	v_trunc_f32_e32 v16, v16
	v_mul_f32_e32 v17, 0x2f800000, v16
	v_floor_f32_e32 v17, v17
	v_fmac_f32_e32 v16, 0xcf800000, v17
	v_cvt_u32_f32_e32 v16, v16
	v_cvt_u32_f32_e32 v17, v17
	global_atomic_add_x2 v[112:113], v[16:17], off offset:1280
.LBB0_583:
	s_or_b64 exec, exec, s[28:29]
	s_mov_b64 s[28:29], 0x2c000
	v_lshl_add_u64 v[24:25], v[138:139], 0, s[28:29]
	v_lshlrev_b64 v[26:27], 2, v[24:25]
	v_lshl_add_u64 v[28:29], s[16:17], 0, v[26:27]
	s_waitcnt lgkmcnt(0)
	s_waitcnt vmcnt(8)
	s_nop 1
	v_mov_b32_e32 v16, v216
	v_mov_b32_e32 v17, v217
	v_mov_b32_e32 v18, v218
	v_mov_b32_e32 v19, v219
	s_nop 1
	v_mov_b32_e32 v20, v220
	v_mov_b32_e32 v21, v221
	v_mov_b32_e32 v22, v222
	v_mov_b32_e32 v23, v223
	v_lshl_add_u64 v[24:25], v[24:25], 1, s[18:19]
	v_lshl_add_u64 v[26:27], s[12:13], 0, v[26:27]
	v_pk_add_f32 v[14:15], v[14:15], v[18:19]
	v_pk_add_f32 v[12:13], v[12:13], v[16:17]
	v_pk_add_f32 v[10:11], v[10:11], v[22:23]
	v_pk_add_f32 v[8:9], v[8:9], v[20:21]
	v_cvt_pk_bf16_f32 v16, v12, v13
	v_cvt_pk_bf16_f32 v17, v14, v15
	v_cvt_pk_bf16_f32 v18, v8, v9
	v_cvt_pk_bf16_f32 v19, v10, v11
	global_store_dwordx4 v[26:27], v[12:15], off
	global_store_dwordx4 v[26:27], v[8:11], off offset:16
	global_store_dwordx4 v[24:25], v[16:19], off
	s_nop 1
	v_mov_b32_e32 v16, v224
	v_mov_b32_e32 v17, v225
	v_mov_b32_e32 v18, v226
	v_mov_b32_e32 v19, v227
	s_nop 0
	s_nop 1
	v_mov_b32_e32 v20, v228
	v_mov_b32_e32 v21, v229
	v_mov_b32_e32 v22, v230
	v_mov_b32_e32 v23, v231
	v_mul_f32_e32 v13, v13, v13
	v_mul_f32_e32 v15, v15, v15
	v_mul_f32_e32 v9, v9, v9
	v_fmac_f32_e32 v13, v12, v12
	v_fmac_f32_e32 v15, v14, v14
	v_mul_f32_e32 v11, v11, v11
	v_fmac_f32_e32 v9, v8, v8
	v_add_f32_e32 v8, v13, v15
	v_fmac_f32_e32 v11, v10, v10
	v_add_f32_e32 v8, v8, v9
	v_add_f32_e32 v12, v11, v8
	v_pk_add_f32 v[6:7], v[6:7], v[18:19]
	v_pk_add_f32 v[4:5], v[4:5], v[16:17]
	v_pk_add_f32 v[10:11], v[2:3], v[22:23]
	v_pk_add_f32 v[8:9], v[0:1], v[20:21]
	v_mul_f32_e32 v1, v5, v5
	v_mul_f32_e32 v2, v7, v7
	v_mul_f32_e32 v3, v9, v9
	v_fmac_f32_e32 v1, v4, v4
	v_fmac_f32_e32 v2, v6, v6
	v_mul_f32_e32 v0, v11, v11
	v_add_f32_e32 v1, v1, v2
	v_fmac_f32_e32 v3, v8, v8
	v_fmac_f32_e32 v0, v10, v10
	v_add_f32_e32 v1, v1, v3
	v_add_f32_e32 v0, v0, v1
	v_add_f32_e32 v0, v12, v0
	ds_bpermute_b32 v1, v180, v0
	global_store_dwordx4 v[26:27], v[4:7], off offset:512
	global_store_dwordx4 v[26:27], v[8:11], off offset:528
	v_cvt_pk_bf16_f32 v2, v4, v5
	v_cvt_pk_bf16_f32 v3, v6, v7
	v_cvt_pk_bf16_f32 v4, v8, v9
	s_waitcnt lgkmcnt(0)
	v_add_f32_e32 v0, v0, v1
	ds_bpermute_b32 v1, v181, v0
	v_cvt_pk_bf16_f32 v5, v10, v11
	global_store_dwordx4 v[24:25], v[2:5], off offset:256
	s_and_saveexec_b64 s[28:29], s[8:9]
	s_cbranch_execz .LBB0_560
	s_waitcnt lgkmcnt(0)
	v_add_f32_e32 v0, v0, v1
	v_fma_f32 v0, v0, s65, 0.5
	v_trunc_f32_e32 v0, v0
	v_mul_f32_e32 v1, 0x2f800000, v0
	v_floor_f32_e32 v1, v1
	v_fmac_f32_e32 v0, 0xcf800000, v1
	v_cvt_u32_f32_e32 v0, v0
	v_cvt_u32_f32_e32 v1, v1
	global_atomic_add_x2 v[112:113], v[0:1], off offset:1408
	s_branch .LBB0_560

.LBB0_725:
	s_add_u32 s26, s24, 0xfff00080
	s_addc_u32 s27, s25, -1
	s_add_i32 s63, s44, 0x120
	s_cmp_eq_u32 s62, 60
	s_cselect_b32 s29, s19, s27
	s_cselect_b32 s28, s58, s26
	s_cselect_b32 s27, s17, s61
	s_cselect_b32 s26, s59, s60
	s_add_i32 s68, s45, 0x120
	v_add_u32_e32 v154, s63, v147
	v_add_u32_e32 v158, s68, v147
	ds_read_b128 v[138:141], v154
	ds_read_b128 v[142:145], v154 offset:1024
	ds_read_b128 v[150:153], v154 offset:2048
	ds_read_b128 v[154:157], v154 offset:3072
	ds_read_b128 v[200:203], v158
	ds_read_b128 v[204:207], v158 offset:1024
	ds_read_b128 v[208:211], v158 offset:2048
	ds_read_b128 v[212:215], v158 offset:3072
	v_lshl_add_u64 v[158:159], s[24:25], 0, v[134:135]
	s_add_i32 m0, s43, 0xc000
	ds_read_b128 v[216:219], v149
	ds_read_b128 v[220:223], v149 offset:1024
	ds_read_b128 v[224:227], v149 offset:2048
	ds_read_b128 v[228:231], v149 offset:3072
	ds_read_b128 v[232:235], v149 offset:4096
	ds_read_b128 v[236:239], v149 offset:5120
	ds_read_b128 v[240:243], v149 offset:6144
	ds_read_b128 v[244:247], v149 offset:7168
	global_load_lds_dwordx4 v[158:159], off
	v_lshl_add_u64 v[158:159], s[24:25], 0, v[136:137]
	s_add_i32 m0, s43, 0xe000
	s_nop 0
	global_load_lds_dwordx4 v[158:159], off
	s_waitcnt vmcnt(8)
	s_waitcnt lgkmcnt(0)
	s_barrier
	s_setprio 1
	s_waitcnt lgkmcnt(0)
	v_mfma_f32_16x16x32_bf16 v[124:127], v[138:141], v[216:219], v[124:127]
	v_mfma_f32_16x16x32_bf16 v[120:123], v[150:153], v[216:219], v[120:123]
	v_mfma_f32_16x16x32_bf16 v[108:111], v[138:141], v[224:227], v[108:111]
	v_mfma_f32_16x16x32_bf16 v[104:107], v[150:153], v[224:227], v[104:107]
	v_mfma_f32_16x16x32_bf16 v[92:95], v[138:141], v[232:235], v[92:95]
	v_mfma_f32_16x16x32_bf16 v[88:91], v[150:153], v[232:235], v[88:91]
	v_mfma_f32_16x16x32_bf16 v[76:79], v[138:141], v[240:243], v[76:79]
	v_mfma_f32_16x16x32_bf16 v[72:75], v[150:153], v[240:243], v[72:75]
	v_mfma_f32_16x16x32_bf16 v[124:127], v[142:145], v[220:223], v[124:127]
	v_mfma_f32_16x16x32_bf16 v[120:123], v[154:157], v[220:223], v[120:123]
	v_mfma_f32_16x16x32_bf16 v[108:111], v[142:145], v[228:231], v[108:111]
	v_mfma_f32_16x16x32_bf16 v[104:107], v[154:157], v[228:231], v[104:107]
	v_mfma_f32_16x16x32_bf16 v[92:95], v[142:145], v[236:239], v[92:95]
	v_mfma_f32_16x16x32_bf16 v[88:91], v[154:157], v[236:239], v[88:91]
	v_mfma_f32_16x16x32_bf16 v[76:79], v[142:145], v[244:247], v[76:79]
	v_mfma_f32_16x16x32_bf16 v[72:75], v[154:157], v[244:247], v[72:75]
	s_setprio 0
	s_setprio 1
	v_mfma_f32_16x16x32_bf16 v[116:119], v[200:203], v[216:219], v[116:119]
	v_mfma_f32_16x16x32_bf16 v[112:115], v[208:211], v[216:219], v[112:115]
	v_mfma_f32_16x16x32_bf16 v[100:103], v[200:203], v[224:227], v[100:103]
	v_mfma_f32_16x16x32_bf16 v[96:99], v[208:211], v[224:227], v[96:99]
	v_mfma_f32_16x16x32_bf16 v[84:87], v[200:203], v[232:235], v[84:87]
	v_mfma_f32_16x16x32_bf16 v[80:83], v[208:211], v[232:235], v[80:83]
	v_mfma_f32_16x16x32_bf16 v[68:71], v[200:203], v[240:243], v[68:71]
	v_mfma_f32_16x16x32_bf16 v[64:67], v[208:211], v[240:243], v[64:67]
	v_mfma_f32_16x16x32_bf16 v[116:119], v[204:207], v[220:223], v[116:119]
	v_mfma_f32_16x16x32_bf16 v[112:115], v[212:215], v[220:223], v[112:115]
	v_mfma_f32_16x16x32_bf16 v[100:103], v[204:207], v[228:231], v[100:103]
	v_mfma_f32_16x16x32_bf16 v[96:99], v[212:215], v[228:231], v[96:99]
	v_mfma_f32_16x16x32_bf16 v[84:87], v[204:207], v[236:239], v[84:87]
	v_mfma_f32_16x16x32_bf16 v[80:83], v[212:215], v[236:239], v[80:83]
	v_mfma_f32_16x16x32_bf16 v[68:71], v[204:207], v[244:247], v[68:71]
	v_mfma_f32_16x16x32_bf16 v[64:67], v[212:215], v[244:247], v[64:67]
	s_setprio 0
	s_barrier
	s_add_i32 s63, s63, s42
	v_lshl_add_u64 v[158:159], s[26:27], 0, v[160:161]
	s_mov_b32 m0, s63
	ds_read_b128 v[216:219], v149 offset:16384
	ds_read_b128 v[220:223], v149 offset:17408
	ds_read_b128 v[224:227], v149 offset:18432
	ds_read_b128 v[228:231], v149 offset:19456
	ds_read_b128 v[232:235], v149 offset:20480
	ds_read_b128 v[236:239], v149 offset:21504
	ds_read_b128 v[240:243], v149 offset:22528
	ds_read_b128 v[244:247], v149 offset:23552
	global_load_lds_dwordx4 v[158:159], off
	s_add_i32 m0, s63, 0x2000
	s_add_u32 s66, s26, 0x100000
	v_lshl_add_u64 v[170:171], s[26:27], 0, v[128:129]
	s_addc_u32 s67, s27, 0
	s_add_i32 s63, s68, s42
	global_load_lds_dwordx4 v[170:171], off
	v_lshl_add_u64 v[174:175], s[66:67], 0, v[160:161]
	s_mov_b32 m0, s63
	v_lshl_add_u64 v[198:199], s[28:29], 0, v[130:131]
	global_load_lds_dwordx4 v[174:175], off
	v_lshl_add_u64 v[174:175], s[66:67], 0, v[128:129]
	s_add_i32 m0, s63, 0x2000
	s_nop 0
	global_load_lds_dwordx4 v[174:175], off
	v_lshl_add_u64 v[174:175], s[28:29], 0, v[132:133]
	s_mov_b32 m0, s43
	s_nop 0
	global_load_lds_dwordx4 v[174:175], off
	s_mov_b32 m0, s48
	s_nop 0
	global_load_lds_dwordx4 v[198:199], off
	s_waitcnt vmcnt(8)
	s_waitcnt lgkmcnt(0)
	s_barrier
	s_setprio 1
	s_waitcnt lgkmcnt(0)
	v_mfma_f32_16x16x32_bf16 v[60:63], v[138:141], v[216:219], v[60:63]
	v_mfma_f32_16x16x32_bf16 v[56:59], v[150:153], v[216:219], v[56:59]
	v_mfma_f32_16x16x32_bf16 v[44:47], v[138:141], v[224:227], v[44:47]
	v_mfma_f32_16x16x32_bf16 v[40:43], v[150:153], v[224:227], v[40:43]
	v_mfma_f32_16x16x32_bf16 v[28:31], v[138:141], v[232:235], v[28:31]
	v_mfma_f32_16x16x32_bf16 v[24:27], v[150:153], v[232:235], v[24:27]
	v_mfma_f32_16x16x32_bf16 v[12:15], v[138:141], v[240:243], v[12:15]
	v_mfma_f32_16x16x32_bf16 v[8:11], v[150:153], v[240:243], v[8:11]
	v_mfma_f32_16x16x32_bf16 v[60:63], v[142:145], v[220:223], v[60:63]
	v_mfma_f32_16x16x32_bf16 v[56:59], v[154:157], v[220:223], v[56:59]
	v_mfma_f32_16x16x32_bf16 v[44:47], v[142:145], v[228:231], v[44:47]
	v_mfma_f32_16x16x32_bf16 v[40:43], v[154:157], v[228:231], v[40:43]
	v_mfma_f32_16x16x32_bf16 v[28:31], v[142:145], v[236:239], v[28:31]
	v_mfma_f32_16x16x32_bf16 v[24:27], v[154:157], v[236:239], v[24:27]
	v_mfma_f32_16x16x32_bf16 v[12:15], v[142:145], v[244:247], v[12:15]
	v_mfma_f32_16x16x32_bf16 v[8:11], v[154:157], v[244:247], v[8:11]
	s_setprio 0
	s_setprio 1
	v_mfma_f32_16x16x32_bf16 v[52:55], v[200:203], v[216:219], v[52:55]
	v_mfma_f32_16x16x32_bf16 v[48:51], v[208:211], v[216:219], v[48:51]
	v_mfma_f32_16x16x32_bf16 v[36:39], v[200:203], v[224:227], v[36:39]
	v_mfma_f32_16x16x32_bf16 v[32:35], v[208:211], v[224:227], v[32:35]
	v_mfma_f32_16x16x32_bf16 v[20:23], v[200:203], v[232:235], v[20:23]
	v_mfma_f32_16x16x32_bf16 v[16:19], v[208:211], v[232:235], v[16:19]
	v_mfma_f32_16x16x32_bf16 v[4:7], v[200:203], v[240:243], v[4:7]
	v_mfma_f32_16x16x32_bf16 v[0:3], v[208:211], v[240:243], v[0:3]
	v_mfma_f32_16x16x32_bf16 v[52:55], v[204:207], v[220:223], v[52:55]
	v_mfma_f32_16x16x32_bf16 v[48:51], v[212:215], v[220:223], v[48:51]
	v_mfma_f32_16x16x32_bf16 v[36:39], v[204:207], v[228:231], v[36:39]
	v_mfma_f32_16x16x32_bf16 v[32:35], v[212:215], v[228:231], v[32:35]
	v_mfma_f32_16x16x32_bf16 v[20:23], v[204:207], v[236:239], v[20:23]
	v_mfma_f32_16x16x32_bf16 v[16:19], v[212:215], v[236:239], v[16:19]
	v_mfma_f32_16x16x32_bf16 v[4:7], v[204:207], v[244:247], v[4:7]
	v_mfma_f32_16x16x32_bf16 v[0:3], v[212:215], v[244:247], v[0:3]
	s_setprio 0
	s_barrier
	s_add_i32 s63, s46, 0x120
	s_add_i32 s66, s47, 0x120
	v_add_u32_e32 v154, s63, v147
	v_add_u32_e32 v172, s66, v147
	ds_read_b128 v[138:141], v154
	ds_read_b128 v[142:145], v154 offset:1024
	ds_read_b128 v[150:153], v154 offset:2048
	ds_read_b128 v[154:157], v154 offset:3072
	ds_read_b128 v[200:203], v172
	ds_read_b128 v[204:207], v172 offset:1024
	ds_read_b128 v[208:211], v172 offset:2048
	ds_read_b128 v[212:215], v172 offset:3072
	s_add_u32 s28, s28, 0x100000
	s_addc_u32 s29, s29, 0
	s_mov_b32 m0, s49
	v_lshl_add_u64 v[248:249], s[28:29], 0, v[132:133]
	ds_read_b128 v[216:219], v149 offset:32768
	ds_read_b128 v[220:223], v149 offset:33792
	ds_read_b128 v[224:227], v149 offset:34816
	ds_read_b128 v[228:231], v149 offset:35840
	ds_read_b128 v[232:235], v149 offset:36864
	ds_read_b128 v[236:239], v149 offset:37888
	ds_read_b128 v[240:243], v149 offset:38912
	ds_read_b128 v[244:247], v149 offset:39936
	global_load_lds_dwordx4 v[248:249], off
	v_lshl_add_u64 v[248:249], s[28:29], 0, v[130:131]
	s_mov_b32 m0, s52
	s_nop 0
	global_load_lds_dwordx4 v[248:249], off
	s_waitcnt vmcnt(8)
	s_waitcnt lgkmcnt(0)
	s_barrier
	s_setprio 1
	s_waitcnt lgkmcnt(0)
	v_mfma_f32_16x16x32_bf16 v[124:127], v[138:141], v[216:219], v[124:127]
	v_mfma_f32_16x16x32_bf16 v[120:123], v[150:153], v[216:219], v[120:123]
	v_mfma_f32_16x16x32_bf16 v[108:111], v[138:141], v[224:227], v[108:111]
	v_mfma_f32_16x16x32_bf16 v[104:107], v[150:153], v[224:227], v[104:107]
	v_mfma_f32_16x16x32_bf16 v[92:95], v[138:141], v[232:235], v[92:95]
	v_mfma_f32_16x16x32_bf16 v[88:91], v[150:153], v[232:235], v[88:91]
	v_mfma_f32_16x16x32_bf16 v[76:79], v[138:141], v[240:243], v[76:79]
	v_mfma_f32_16x16x32_bf16 v[72:75], v[150:153], v[240:243], v[72:75]
	v_mfma_f32_16x16x32_bf16 v[124:127], v[142:145], v[220:223], v[124:127]
	v_mfma_f32_16x16x32_bf16 v[120:123], v[154:157], v[220:223], v[120:123]
	v_mfma_f32_16x16x32_bf16 v[108:111], v[142:145], v[228:231], v[108:111]
	v_mfma_f32_16x16x32_bf16 v[104:107], v[154:157], v[228:231], v[104:107]
	v_mfma_f32_16x16x32_bf16 v[92:95], v[142:145], v[236:239], v[92:95]
	v_mfma_f32_16x16x32_bf16 v[88:91], v[154:157], v[236:239], v[88:91]
	v_mfma_f32_16x16x32_bf16 v[76:79], v[142:145], v[244:247], v[76:79]
	v_mfma_f32_16x16x32_bf16 v[72:75], v[154:157], v[244:247], v[72:75]
	s_setprio 0
	s_setprio 1
	v_mfma_f32_16x16x32_bf16 v[116:119], v[200:203], v[216:219], v[116:119]
	v_mfma_f32_16x16x32_bf16 v[112:115], v[208:211], v[216:219], v[112:115]
	v_mfma_f32_16x16x32_bf16 v[100:103], v[200:203], v[224:227], v[100:103]
	v_mfma_f32_16x16x32_bf16 v[96:99], v[208:211], v[224:227], v[96:99]
	v_mfma_f32_16x16x32_bf16 v[84:87], v[200:203], v[232:235], v[84:87]
	v_mfma_f32_16x16x32_bf16 v[80:83], v[208:211], v[232:235], v[80:83]
	v_mfma_f32_16x16x32_bf16 v[68:71], v[200:203], v[240:243], v[68:71]
	v_mfma_f32_16x16x32_bf16 v[64:67], v[208:211], v[240:243], v[64:67]
	v_mfma_f32_16x16x32_bf16 v[116:119], v[204:207], v[220:223], v[116:119]
	v_mfma_f32_16x16x32_bf16 v[112:115], v[212:215], v[220:223], v[112:115]
	v_mfma_f32_16x16x32_bf16 v[100:103], v[204:207], v[228:231], v[100:103]
	v_mfma_f32_16x16x32_bf16 v[96:99], v[212:215], v[228:231], v[96:99]
	v_mfma_f32_16x16x32_bf16 v[84:87], v[204:207], v[236:239], v[84:87]
	v_mfma_f32_16x16x32_bf16 v[80:83], v[212:215], v[236:239], v[80:83]
	v_mfma_f32_16x16x32_bf16 v[68:71], v[204:207], v[244:247], v[68:71]
	v_mfma_f32_16x16x32_bf16 v[64:67], v[212:215], v[244:247], v[64:67]
	s_setprio 0
	s_barrier
	s_add_i32 s28, s63, s42
	v_lshl_add_u64 v[158:159], v[158:159], 0, s[88:89]
	s_mov_b32 m0, s28
	ds_read_b128 v[216:219], v149 offset:49152
	ds_read_b128 v[220:223], v149 offset:50176
	ds_read_b128 v[224:227], v149 offset:51200
	ds_read_b128 v[228:231], v149 offset:52224
	ds_read_b128 v[232:235], v149 offset:53248
	ds_read_b128 v[236:239], v149 offset:54272
	ds_read_b128 v[240:243], v149 offset:55296
	ds_read_b128 v[244:247], v149 offset:56320
	global_load_lds_dwordx4 v[158:159], off
	s_add_i32 m0, s28, 0x2000
	s_add_u32 s26, s26, 0x100080
	v_lshl_add_u64 v[158:159], v[170:171], 0, s[88:89]
	s_addc_u32 s27, s27, 0
	s_add_i32 s28, s66, s42
	global_load_lds_dwordx4 v[158:159], off
	v_lshl_add_u64 v[158:159], s[26:27], 0, v[160:161]
	s_mov_b32 m0, s28
	s_nop 0
	global_load_lds_dwordx4 v[158:159], off
	v_lshl_add_u64 v[158:159], s[26:27], 0, v[128:129]
	s_add_i32 m0, s28, 0x2000
	s_nop 0
	global_load_lds_dwordx4 v[158:159], off
	v_lshl_add_u64 v[158:159], v[174:175], 0, s[88:89]
	s_mov_b32 m0, s53
	s_nop 0
	global_load_lds_dwordx4 v[158:159], off
	v_lshl_add_u64 v[158:159], v[198:199], 0, s[88:89]
	s_mov_b32 m0, s56
	s_nop 0
	global_load_lds_dwordx4 v[158:159], off
	s_waitcnt vmcnt(8)
	s_waitcnt lgkmcnt(0)
	s_barrier
	s_setprio 1
	s_waitcnt lgkmcnt(0)
	v_mfma_f32_16x16x32_bf16 v[60:63], v[138:141], v[216:219], v[60:63]
	v_mfma_f32_16x16x32_bf16 v[56:59], v[150:153], v[216:219], v[56:59]
	v_mfma_f32_16x16x32_bf16 v[44:47], v[138:141], v[224:227], v[44:47]
	v_mfma_f32_16x16x32_bf16 v[40:43], v[150:153], v[224:227], v[40:43]
	v_mfma_f32_16x16x32_bf16 v[28:31], v[138:141], v[232:235], v[28:31]
	v_mfma_f32_16x16x32_bf16 v[24:27], v[150:153], v[232:235], v[24:27]
	v_mfma_f32_16x16x32_bf16 v[12:15], v[138:141], v[240:243], v[12:15]
	v_mfma_f32_16x16x32_bf16 v[8:11], v[150:153], v[240:243], v[8:11]
	v_mfma_f32_16x16x32_bf16 v[60:63], v[142:145], v[220:223], v[60:63]
	v_mfma_f32_16x16x32_bf16 v[56:59], v[154:157], v[220:223], v[56:59]
	v_mfma_f32_16x16x32_bf16 v[44:47], v[142:145], v[228:231], v[44:47]
	v_mfma_f32_16x16x32_bf16 v[40:43], v[154:157], v[228:231], v[40:43]
	v_mfma_f32_16x16x32_bf16 v[28:31], v[142:145], v[236:239], v[28:31]
	v_mfma_f32_16x16x32_bf16 v[24:27], v[154:157], v[236:239], v[24:27]
	v_mfma_f32_16x16x32_bf16 v[12:15], v[142:145], v[244:247], v[12:15]
	v_mfma_f32_16x16x32_bf16 v[8:11], v[154:157], v[244:247], v[8:11]
	s_setprio 0
	s_setprio 1
	v_mfma_f32_16x16x32_bf16 v[52:55], v[200:203], v[216:219], v[52:55]
	v_mfma_f32_16x16x32_bf16 v[48:51], v[208:211], v[216:219], v[48:51]
	v_mfma_f32_16x16x32_bf16 v[36:39], v[200:203], v[224:227], v[36:39]
	v_mfma_f32_16x16x32_bf16 v[32:35], v[208:211], v[224:227], v[32:35]
	v_mfma_f32_16x16x32_bf16 v[20:23], v[200:203], v[232:235], v[20:23]
	v_mfma_f32_16x16x32_bf16 v[16:19], v[208:211], v[232:235], v[16:19]
	v_mfma_f32_16x16x32_bf16 v[4:7], v[200:203], v[240:243], v[4:7]
	v_mfma_f32_16x16x32_bf16 v[0:3], v[208:211], v[240:243], v[0:3]
	v_mfma_f32_16x16x32_bf16 v[52:55], v[204:207], v[220:223], v[52:55]
	v_mfma_f32_16x16x32_bf16 v[48:51], v[212:215], v[220:223], v[48:51]
	v_mfma_f32_16x16x32_bf16 v[36:39], v[204:207], v[228:231], v[36:39]
	v_mfma_f32_16x16x32_bf16 v[32:35], v[212:215], v[228:231], v[32:35]
	v_mfma_f32_16x16x32_bf16 v[20:23], v[204:207], v[236:239], v[20:23]
	v_mfma_f32_16x16x32_bf16 v[16:19], v[212:215], v[236:239], v[16:19]
	v_mfma_f32_16x16x32_bf16 v[4:7], v[204:207], v[244:247], v[4:7]
	v_mfma_f32_16x16x32_bf16 v[0:3], v[212:215], v[244:247], v[0:3]
	s_setprio 0
	s_barrier
	s_add_i32 s62, s62, 2
	s_add_u32 s24, s24, 0x100
	s_addc_u32 s25, s25, 0
	s_add_u32 s60, s60, 0x100
	s_addc_u32 s61, s61, 0
	s_cmp_gt_u32 s62, 61
	s_cbranch_scc0 .LBB0_725
	v_lshl_add_u32 v138, s51, 8, v146
	v_lshl_or_b32 v142, s1, 8, v148
	v_ashrrev_i32_e32 v139, 31, v138
	v_ashrrev_i32_e32 v143, 31, v142
	v_lshlrev_b64 v[140:141], 10, v[138:139]
	v_lshl_add_u64 v[140:141], v[140:141], 0, v[142:143]
	v_lshl_add_u64 v[144:145], v[140:141], 2, s[12:13]
	v_mov_b32_e32 v248, v144
	v_mov_b32_e32 v249, v145
	global_load_dwordx4 v[200:203], v[248:249], off
	global_load_dwordx4 v[204:207], v[248:249], off offset:16
	global_load_dwordx4 v[208:211], v[248:249], off offset:512
	global_load_dwordx4 v[212:215], v[248:249], off offset:528
	s_mov_b64 s[98:99], 0x10000
	v_lshl_add_u64 v[250:251], v[248:249], 0, s[98:99]
	global_load_dwordx4 v[216:219], v[250:251], off
	global_load_dwordx4 v[220:223], v[250:251], off offset:16
	global_load_dwordx4 v[224:227], v[250:251], off offset:512
	global_load_dwordx4 v[228:231], v[250:251], off offset:528
	s_mov_b64 s[98:99], 0x20000
	v_lshl_add_u64 v[250:251], v[248:249], 0, s[98:99]
	global_load_dwordx4 v[232:235], v[250:251], off
	global_load_dwordx4 v[236:239], v[250:251], off offset:16
	global_load_dwordx4 v[240:243], v[250:251], off offset:512
	global_load_dwordx4 v[244:247], v[250:251], off offset:528
	s_waitcnt vmcnt(8)
	s_nop 1
	v_mov_b32_e32 v150, v200
	v_mov_b32_e32 v151, v201
	v_mov_b32_e32 v152, v202
	v_mov_b32_e32 v153, v203
	s_nop 1
	v_mov_b32_e32 v154, v204
	v_mov_b32_e32 v155, v205
	v_mov_b32_e32 v156, v206
	v_mov_b32_e32 v157, v207
	s_mov_b64 s[24:25], -1
	s_and_b64 vcc, exec, s[4:5]
	v_pk_add_f32 v[126:127], v[126:127], v[152:153]
	v_pk_add_f32 v[124:125], v[124:125], v[150:151]
	v_pk_add_f32 v[122:123], v[122:123], v[156:157]
	v_pk_add_f32 v[120:121], v[120:121], v[154:155]
	global_store_dwordx4 v[144:145], v[124:127], off
	global_store_dwordx4 v[144:145], v[120:123], off offset:16
	s_cbranch_vccz .LBB0_728
	s_nop 1
	v_mov_b32_e32 v150, v208
	v_mov_b32_e32 v151, v209
	v_mov_b32_e32 v152, v210
	v_mov_b32_e32 v153, v211
	s_nop 1
	v_mov_b32_e32 v154, v212
	v_mov_b32_e32 v155, v213
	v_mov_b32_e32 v156, v214
	v_mov_b32_e32 v157, v215
	s_mov_b64 s[24:25], 0
	v_pk_add_f32 v[152:153], v[118:119], v[152:153]
	v_pk_add_f32 v[150:151], v[116:117], v[150:151]
	v_pk_add_f32 v[156:157], v[114:115], v[156:157]
	v_pk_add_f32 v[154:155], v[112:113], v[154:155]
	global_store_dwordx4 v[144:145], v[150:153], off offset:512
	global_store_dwordx4 v[144:145], v[154:157], off offset:528
.LBB0_728:
	s_andn2_b64 vcc, exec, s[24:25]
	s_cbranch_vccnz .LBB0_732
	v_cvt_pk_bf16_f32 v150, v124, v125
	v_mul_f32_e32 v125, v125, v125
	v_fmac_f32_e32 v125, v124, v124
	v_mul_f32_e32 v124, v127, v127
	v_cvt_pk_bf16_f32 v152, v120, v121
	v_fmac_f32_e32 v124, v126, v126
	v_mul_f32_e32 v121, v121, v121
	v_add_f32_e32 v124, v125, v124
	v_fmac_f32_e32 v121, v120, v120
	v_cvt_pk_bf16_f32 v151, v126, v127
	v_cvt_pk_bf16_f32 v153, v122, v123
	v_lshl_add_u64 v[154:155], v[140:141], 1, s[10:11]
	v_add_f32_e32 v120, v124, v121
	v_mul_f32_e32 v121, v123, v123
	global_store_dwordx4 v[154:155], v[150:153], off
	v_fmac_f32_e32 v121, v122, v122
	s_nop 0
	v_add_f32_e32 v150, v121, v120
	s_nop 1
	v_mov_b32_e32 v120, v212
	v_mov_b32_e32 v121, v213
	v_mov_b32_e32 v122, v214
	v_mov_b32_e32 v123, v215
	s_nop 1
	v_mov_b32_e32 v124, v208
	v_mov_b32_e32 v125, v209
	v_mov_b32_e32 v126, v210
	v_mov_b32_e32 v127, v211
	v_pk_add_f32 v[114:115], v[114:115], v[122:123]
	v_pk_add_f32 v[118:119], v[118:119], v[126:127]
	v_pk_add_f32 v[116:117], v[116:117], v[124:125]
	v_pk_add_f32 v[112:113], v[112:113], v[120:121]
	global_store_dwordx4 v[144:145], v[116:119], off offset:512
	global_store_dwordx4 v[144:145], v[112:115], off offset:528
	v_cvt_pk_bf16_f32 v123, v114, v115
	v_cvt_pk_bf16_f32 v120, v116, v117
	v_mul_f32_e32 v115, v115, v115
	v_fmac_f32_e32 v115, v114, v114
	v_mul_f32_e32 v114, v117, v117
	v_fmac_f32_e32 v114, v116, v116
	v_mul_f32_e32 v116, v119, v119
	v_cvt_pk_bf16_f32 v122, v112, v113
	v_fmac_f32_e32 v116, v118, v118
	v_mul_f32_e32 v113, v113, v113
	v_add_f32_e32 v114, v114, v116
	v_fmac_f32_e32 v113, v112, v112
	v_add_f32_e32 v112, v114, v113
	v_add_f32_e32 v112, v115, v112
	v_add_f32_e32 v112, v150, v112
	ds_bpermute_b32 v113, v180, v112
	v_cvt_pk_bf16_f32 v121, v118, v119
	global_store_dwordx4 v[154:155], v[120:123], off offset:256
	s_waitcnt lgkmcnt(0)
	v_add_f32_e32 v112, v112, v113
	ds_bpermute_b32 v113, v181, v112
	s_and_saveexec_b64 s[24:25], s[6:7]
	s_cbranch_execz .LBB0_731
	s_waitcnt lgkmcnt(0)
	v_add_f32_e32 v112, v112, v113
	v_fma_f32 v112, v112, s65, 0.5
	v_trunc_f32_e32 v112, v112
	v_mul_f32_e32 v113, 0x2f800000, v112
	v_floor_f32_e32 v113, v113
	v_fmac_f32_e32 v112, 0xcf800000, v113
	v_cvt_u32_f32_e32 v112, v112
	v_cvt_u32_f32_e32 v113, v113
	v_lshl_add_u64 v[114:115], v[138:139], 3, s[14:15]
	global_atomic_add_x2 v[114:115], v[112:113], off

.LBB0_732:
	v_or_b32_e32 v112, 16, v138
	s_waitcnt lgkmcnt(0)
	v_ashrrev_i32_e32 v113, 31, v112
	v_lshlrev_b64 v[112:113], 10, v[112:113]
	v_lshl_add_u64 v[114:115], v[112:113], 0, v[142:143]
	v_lshl_add_u64 v[112:113], v[114:115], 2, s[12:13]
	s_mov_b64 s[98:99], 0x30000
	v_lshl_add_u64 v[250:251], v[248:249], 0, s[98:99]
	global_load_dwordx4 v[200:203], v[250:251], off
	global_load_dwordx4 v[204:207], v[250:251], off offset:16
	global_load_dwordx4 v[208:211], v[250:251], off offset:512
	global_load_dwordx4 v[212:215], v[250:251], off offset:528
	s_waitcnt vmcnt(12)
	s_nop 1
	v_mov_b32_e32 v116, v216
	v_mov_b32_e32 v117, v217
	v_mov_b32_e32 v118, v218
	v_mov_b32_e32 v119, v219
	s_nop 1
	v_mov_b32_e32 v120, v220
	v_mov_b32_e32 v121, v221
	v_mov_b32_e32 v122, v222
	v_mov_b32_e32 v123, v223
	s_mov_b64 s[24:25], -1
	s_and_b64 vcc, exec, s[4:5]
	v_pk_add_f32 v[110:111], v[110:111], v[118:119]
	v_pk_add_f32 v[108:109], v[108:109], v[116:117]
	v_pk_add_f32 v[106:107], v[106:107], v[122:123]
	v_pk_add_f32 v[104:105], v[104:105], v[120:121]
	global_store_dwordx4 v[112:113], v[108:111], off
	global_store_dwordx4 v[112:113], v[104:107], off offset:16
	s_cbranch_vccz .LBB0_734
	s_nop 1
	v_mov_b32_e32 v116, v224
	v_mov_b32_e32 v117, v225
	v_mov_b32_e32 v118, v226
	v_mov_b32_e32 v119, v227
	s_nop 1
	v_mov_b32_e32 v120, v228
	v_mov_b32_e32 v121, v229
	v_mov_b32_e32 v122, v230
	v_mov_b32_e32 v123, v231
	s_mov_b64 s[24:25], 0
	v_pk_add_f32 v[118:119], v[102:103], v[118:119]
	v_pk_add_f32 v[116:117], v[100:101], v[116:117]
	v_pk_add_f32 v[122:123], v[98:99], v[122:123]
	v_pk_add_f32 v[120:121], v[96:97], v[120:121]
	global_store_dwordx4 v[112:113], v[116:119], off offset:512
	global_store_dwordx4 v[112:113], v[120:123], off offset:528
.LBB0_734:
	v_readlane_b32 s62, v254, 61
	v_readlane_b32 s66, v254, 63
	s_andn2_b64 vcc, exec, s[24:25]
	v_readlane_b32 s63, v254, 62
	v_readlane_b32 s67, v255, 0
	s_cbranch_vccnz .LBB0_738
	v_cvt_pk_bf16_f32 v116, v108, v109
	v_mul_f32_e32 v109, v109, v109
	v_fmac_f32_e32 v109, v108, v108
	v_mul_f32_e32 v108, v111, v111
	v_cvt_pk_bf16_f32 v118, v104, v105
	v_fmac_f32_e32 v108, v110, v110
	v_mul_f32_e32 v105, v105, v105
	v_add_f32_e32 v108, v109, v108
	v_fmac_f32_e32 v105, v104, v104
	v_cvt_pk_bf16_f32 v117, v110, v111
	v_cvt_pk_bf16_f32 v119, v106, v107
	v_lshl_add_u64 v[114:115], v[114:115], 1, s[10:11]
	v_add_f32_e32 v104, v108, v105
	v_mul_f32_e32 v105, v107, v107
	global_store_dwordx4 v[114:115], v[116:119], off
	v_fmac_f32_e32 v105, v106, v106
	s_nop 0
	v_add_f32_e32 v116, v105, v104
	s_nop 1
	v_mov_b32_e32 v104, v228
	v_mov_b32_e32 v105, v229
	v_mov_b32_e32 v106, v230
	v_mov_b32_e32 v107, v231
	s_nop 1
	v_mov_b32_e32 v108, v224
	v_mov_b32_e32 v109, v225
	v_mov_b32_e32 v110, v226
	v_mov_b32_e32 v111, v227
	v_pk_add_f32 v[98:99], v[98:99], v[106:107]
	v_pk_add_f32 v[102:103], v[102:103], v[110:111]
	v_pk_add_f32 v[100:101], v[100:101], v[108:109]
	v_pk_add_f32 v[96:97], v[96:97], v[104:105]
	global_store_dwordx4 v[112:113], v[100:103], off offset:512
	global_store_dwordx4 v[112:113], v[96:99], off offset:528
	v_cvt_pk_bf16_f32 v107, v98, v99
	v_cvt_pk_bf16_f32 v104, v100, v101
	v_mul_f32_e32 v99, v99, v99
	v_fmac_f32_e32 v99, v98, v98
	v_mul_f32_e32 v98, v101, v101
	v_fmac_f32_e32 v98, v100, v100
	v_mul_f32_e32 v100, v103, v103
	v_cvt_pk_bf16_f32 v106, v96, v97
	v_fmac_f32_e32 v100, v102, v102
	v_mul_f32_e32 v97, v97, v97
	v_add_f32_e32 v98, v98, v100
	v_fmac_f32_e32 v97, v96, v96
	v_add_f32_e32 v96, v98, v97
	v_add_f32_e32 v96, v99, v96
	v_add_f32_e32 v96, v116, v96
	ds_bpermute_b32 v97, v180, v96
	v_cvt_pk_bf16_f32 v105, v102, v103
	global_store_dwordx4 v[114:115], v[104:107], off offset:256
	s_waitcnt lgkmcnt(0)
	v_add_f32_e32 v96, v96, v97
	ds_bpermute_b32 v97, v181, v96
	s_and_saveexec_b64 s[24:25], s[6:7]
	s_cbranch_execz .LBB0_737
	s_waitcnt lgkmcnt(0)
	v_add_f32_e32 v96, v96, v97
	v_fma_f32 v96, v96, s65, 0.5
	v_trunc_f32_e32 v96, v96
	v_mul_f32_e32 v97, 0x2f800000, v96
	v_floor_f32_e32 v97, v97
	v_fmac_f32_e32 v96, 0xcf800000, v97
	v_cvt_u32_f32_e32 v96, v96
	v_cvt_u32_f32_e32 v97, v97
	v_lshl_add_u64 v[98:99], v[138:139], 3, s[14:15]
	global_atomic_add_x2 v[98:99], v[96:97], off offset:128

.LBB0_738:
	v_or_b32_e32 v96, 32, v138
	s_waitcnt lgkmcnt(0)
	v_ashrrev_i32_e32 v97, 31, v96
	v_lshlrev_b64 v[96:97], 10, v[96:97]
	v_lshl_add_u64 v[98:99], v[96:97], 0, v[142:143]
	v_lshl_add_u64 v[96:97], v[98:99], 2, s[12:13]
	s_mov_b64 s[98:99], 0x80000
	v_lshl_add_u64 v[250:251], v[248:249], 0, s[98:99]
	global_load_dwordx4 v[216:219], v[250:251], off
	global_load_dwordx4 v[220:223], v[250:251], off offset:16
	global_load_dwordx4 v[224:227], v[250:251], off offset:512
	global_load_dwordx4 v[228:231], v[250:251], off offset:528
	s_waitcnt vmcnt(16)
	s_nop 1
	v_mov_b32_e32 v100, v232
	v_mov_b32_e32 v101, v233
	v_mov_b32_e32 v102, v234
	v_mov_b32_e32 v103, v235
	s_nop 1
	v_mov_b32_e32 v104, v236
	v_mov_b32_e32 v105, v237
	v_mov_b32_e32 v106, v238
	v_mov_b32_e32 v107, v239
	s_mov_b64 s[24:25], -1
	s_and_b64 vcc, exec, s[4:5]
	v_pk_add_f32 v[94:95], v[94:95], v[102:103]
	v_pk_add_f32 v[92:93], v[92:93], v[100:101]
	v_pk_add_f32 v[90:91], v[90:91], v[106:107]
	v_pk_add_f32 v[88:89], v[88:89], v[104:105]
	global_store_dwordx4 v[96:97], v[92:95], off
	global_store_dwordx4 v[96:97], v[88:91], off offset:16
	s_cbranch_vccz .LBB0_740
	s_nop 1
	v_mov_b32_e32 v100, v240
	v_mov_b32_e32 v101, v241
	v_mov_b32_e32 v102, v242
	v_mov_b32_e32 v103, v243
	s_nop 1
	v_mov_b32_e32 v104, v244
	v_mov_b32_e32 v105, v245
	v_mov_b32_e32 v106, v246
	v_mov_b32_e32 v107, v247
	s_mov_b64 s[24:25], 0
	v_pk_add_f32 v[102:103], v[86:87], v[102:103]
	v_pk_add_f32 v[100:101], v[84:85], v[100:101]
	v_pk_add_f32 v[106:107], v[82:83], v[106:107]
	v_pk_add_f32 v[104:105], v[80:81], v[104:105]
	global_store_dwordx4 v[96:97], v[100:103], off offset:512
	global_store_dwordx4 v[96:97], v[104:107], off offset:528
.LBB0_740:
	s_andn2_b64 vcc, exec, s[24:25]
	s_cbranch_vccnz .LBB0_744
	v_cvt_pk_bf16_f32 v100, v92, v93
	v_mul_f32_e32 v93, v93, v93
	v_fmac_f32_e32 v93, v92, v92
	v_mul_f32_e32 v92, v95, v95
	v_cvt_pk_bf16_f32 v102, v88, v89
	v_fmac_f32_e32 v92, v94, v94
	v_mul_f32_e32 v89, v89, v89
	v_add_f32_e32 v92, v93, v92
	v_fmac_f32_e32 v89, v88, v88
	v_cvt_pk_bf16_f32 v101, v94, v95
	v_cvt_pk_bf16_f32 v103, v90, v91
	v_lshl_add_u64 v[98:99], v[98:99], 1, s[10:11]
	v_add_f32_e32 v88, v92, v89
	v_mul_f32_e32 v89, v91, v91
	global_store_dwordx4 v[98:99], v[100:103], off
	v_fmac_f32_e32 v89, v90, v90
	s_nop 0
	v_add_f32_e32 v100, v89, v88
	s_nop 1
	v_mov_b32_e32 v88, v244
	v_mov_b32_e32 v89, v245
	v_mov_b32_e32 v90, v246
	v_mov_b32_e32 v91, v247
	s_nop 1
	v_mov_b32_e32 v92, v240
	v_mov_b32_e32 v93, v241
	v_mov_b32_e32 v94, v242
	v_mov_b32_e32 v95, v243
	v_pk_add_f32 v[82:83], v[82:83], v[90:91]
	v_pk_add_f32 v[86:87], v[86:87], v[94:95]
	v_pk_add_f32 v[84:85], v[84:85], v[92:93]
	v_pk_add_f32 v[80:81], v[80:81], v[88:89]
	global_store_dwordx4 v[96:97], v[84:87], off offset:512
	global_store_dwordx4 v[96:97], v[80:83], off offset:528
	v_cvt_pk_bf16_f32 v91, v82, v83
	v_cvt_pk_bf16_f32 v88, v84, v85
	v_mul_f32_e32 v83, v83, v83
	v_fmac_f32_e32 v83, v82, v82
	v_mul_f32_e32 v82, v85, v85
	v_fmac_f32_e32 v82, v84, v84
	v_mul_f32_e32 v84, v87, v87
	v_cvt_pk_bf16_f32 v90, v80, v81
	v_fmac_f32_e32 v84, v86, v86
	v_mul_f32_e32 v81, v81, v81
	v_add_f32_e32 v82, v82, v84
	v_fmac_f32_e32 v81, v80, v80
	v_add_f32_e32 v80, v82, v81
	v_add_f32_e32 v80, v83, v80
	v_add_f32_e32 v80, v100, v80
	ds_bpermute_b32 v81, v180, v80
	v_cvt_pk_bf16_f32 v89, v86, v87
	global_store_dwordx4 v[98:99], v[88:91], off offset:256
	s_waitcnt lgkmcnt(0)
	v_add_f32_e32 v80, v80, v81
	ds_bpermute_b32 v81, v181, v80
	s_and_saveexec_b64 s[24:25], s[6:7]
	s_cbranch_execz .LBB0_743
	s_waitcnt lgkmcnt(0)
	v_add_f32_e32 v80, v80, v81
	v_fma_f32 v80, v80, s65, 0.5
	v_trunc_f32_e32 v80, v80
	v_mul_f32_e32 v81, 0x2f800000, v80
	v_floor_f32_e32 v81, v81
	v_fmac_f32_e32 v80, 0xcf800000, v81
	v_cvt_u32_f32_e32 v80, v80
	v_cvt_u32_f32_e32 v81, v81
	v_lshl_add_u64 v[82:83], v[138:139], 3, s[14:15]
	global_atomic_add_x2 v[82:83], v[80:81], off offset:256

.LBB0_744:
	v_or_b32_e32 v80, 48, v138
	s_waitcnt lgkmcnt(0)
	v_ashrrev_i32_e32 v81, 31, v80
	v_lshlrev_b64 v[80:81], 10, v[80:81]
	v_lshl_add_u64 v[82:83], v[80:81], 0, v[142:143]
	v_lshl_add_u64 v[80:81], v[82:83], 2, s[12:13]
	s_mov_b64 s[98:99], 0x90000
	v_lshl_add_u64 v[250:251], v[248:249], 0, s[98:99]
	global_load_dwordx4 v[232:235], v[250:251], off
	global_load_dwordx4 v[236:239], v[250:251], off offset:16
	global_load_dwordx4 v[240:243], v[250:251], off offset:512
	global_load_dwordx4 v[244:247], v[250:251], off offset:528
	s_waitcnt vmcnt(16)
	s_nop 1
	v_mov_b32_e32 v84, v200
	v_mov_b32_e32 v85, v201
	v_mov_b32_e32 v86, v202
	v_mov_b32_e32 v87, v203
	s_nop 1
	v_mov_b32_e32 v88, v204
	v_mov_b32_e32 v89, v205
	v_mov_b32_e32 v90, v206
	v_mov_b32_e32 v91, v207
	s_mov_b64 s[24:25], -1
	s_and_b64 vcc, exec, s[4:5]
	v_pk_add_f32 v[78:79], v[78:79], v[86:87]
	v_pk_add_f32 v[76:77], v[76:77], v[84:85]
	v_pk_add_f32 v[74:75], v[74:75], v[90:91]
	v_pk_add_f32 v[72:73], v[72:73], v[88:89]
	global_store_dwordx4 v[80:81], v[76:79], off
	global_store_dwordx4 v[80:81], v[72:75], off offset:16
	s_cbranch_vccz .LBB0_746
	s_nop 1
	v_mov_b32_e32 v84, v208
	v_mov_b32_e32 v85, v209
	v_mov_b32_e32 v86, v210
	v_mov_b32_e32 v87, v211
	s_nop 1
	v_mov_b32_e32 v88, v212
	v_mov_b32_e32 v89, v213
	v_mov_b32_e32 v90, v214
	v_mov_b32_e32 v91, v215
	s_mov_b64 s[24:25], 0
	v_pk_add_f32 v[86:87], v[70:71], v[86:87]
	v_pk_add_f32 v[84:85], v[68:69], v[84:85]
	v_pk_add_f32 v[90:91], v[66:67], v[90:91]
	v_pk_add_f32 v[88:89], v[64:65], v[88:89]
	global_store_dwordx4 v[80:81], v[84:87], off offset:512
	global_store_dwordx4 v[80:81], v[88:91], off offset:528
.LBB0_746:
	s_andn2_b64 vcc, exec, s[24:25]
	s_cbranch_vccnz .LBB0_750
	v_cvt_pk_bf16_f32 v84, v76, v77
	v_mul_f32_e32 v77, v77, v77
	v_fmac_f32_e32 v77, v76, v76
	v_mul_f32_e32 v76, v79, v79
	v_cvt_pk_bf16_f32 v86, v72, v73
	v_fmac_f32_e32 v76, v78, v78
	v_mul_f32_e32 v73, v73, v73
	v_add_f32_e32 v76, v77, v76
	v_fmac_f32_e32 v73, v72, v72
	v_cvt_pk_bf16_f32 v85, v78, v79
	v_cvt_pk_bf16_f32 v87, v74, v75
	v_lshl_add_u64 v[82:83], v[82:83], 1, s[10:11]
	v_add_f32_e32 v72, v76, v73
	v_mul_f32_e32 v73, v75, v75
	global_store_dwordx4 v[82:83], v[84:87], off
	v_fmac_f32_e32 v73, v74, v74
	s_nop 0
	v_add_f32_e32 v84, v73, v72
	s_nop 1
	v_mov_b32_e32 v72, v212
	v_mov_b32_e32 v73, v213
	v_mov_b32_e32 v74, v214
	v_mov_b32_e32 v75, v215
	s_nop 1
	v_mov_b32_e32 v76, v208
	v_mov_b32_e32 v77, v209
	v_mov_b32_e32 v78, v210
	v_mov_b32_e32 v79, v211
	v_pk_add_f32 v[66:67], v[66:67], v[74:75]
	v_pk_add_f32 v[70:71], v[70:71], v[78:79]
	v_pk_add_f32 v[68:69], v[68:69], v[76:77]
	v_pk_add_f32 v[64:65], v[64:65], v[72:73]
	global_store_dwordx4 v[80:81], v[68:71], off offset:512
	global_store_dwordx4 v[80:81], v[64:67], off offset:528
	v_cvt_pk_bf16_f32 v75, v66, v67
	v_cvt_pk_bf16_f32 v72, v68, v69
	v_mul_f32_e32 v67, v67, v67
	v_fmac_f32_e32 v67, v66, v66
	v_mul_f32_e32 v66, v69, v69
	v_fmac_f32_e32 v66, v68, v68
	v_mul_f32_e32 v68, v71, v71
	v_cvt_pk_bf16_f32 v74, v64, v65
	v_fmac_f32_e32 v68, v70, v70
	v_mul_f32_e32 v65, v65, v65
	v_add_f32_e32 v66, v66, v68
	v_fmac_f32_e32 v65, v64, v64
	v_add_f32_e32 v64, v66, v65
	v_add_f32_e32 v64, v67, v64
	v_add_f32_e32 v64, v84, v64
	ds_bpermute_b32 v65, v180, v64
	v_cvt_pk_bf16_f32 v73, v70, v71
	global_store_dwordx4 v[82:83], v[72:75], off offset:256
	s_waitcnt lgkmcnt(0)
	v_add_f32_e32 v64, v64, v65
	ds_bpermute_b32 v65, v181, v64
	s_and_saveexec_b64 s[24:25], s[6:7]
	s_cbranch_execz .LBB0_749
	s_waitcnt lgkmcnt(0)
	v_add_f32_e32 v64, v64, v65
	v_fma_f32 v64, v64, s65, 0.5
	v_trunc_f32_e32 v64, v64
	v_mul_f32_e32 v65, 0x2f800000, v64
	v_floor_f32_e32 v65, v65
	v_fmac_f32_e32 v64, 0xcf800000, v65
	v_cvt_u32_f32_e32 v64, v64
	v_cvt_u32_f32_e32 v65, v65
	v_lshl_add_u64 v[66:67], v[138:139], 3, s[14:15]
	global_atomic_add_x2 v[66:67], v[64:65], off offset:384

.LBB0_750:
	s_mov_b64 s[24:25], 0x20000
	v_lshl_add_u64 v[66:67], v[140:141], 0, s[24:25]
	s_waitcnt lgkmcnt(0)
	v_lshl_add_u64 v[64:65], v[66:67], 2, s[12:13]
	s_mov_b64 s[98:99], 0xa0000
	v_lshl_add_u64 v[250:251], v[248:249], 0, s[98:99]
	global_load_dwordx4 v[200:203], v[250:251], off
	global_load_dwordx4 v[204:207], v[250:251], off offset:16
	global_load_dwordx4 v[208:211], v[250:251], off offset:512
	global_load_dwordx4 v[212:215], v[250:251], off offset:528
	s_waitcnt vmcnt(16)
	s_nop 1
	v_mov_b32_e32 v68, v216
	v_mov_b32_e32 v69, v217
	v_mov_b32_e32 v70, v218
	v_mov_b32_e32 v71, v219
	s_nop 1
	v_mov_b32_e32 v72, v220
	v_mov_b32_e32 v73, v221
	v_mov_b32_e32 v74, v222
	v_mov_b32_e32 v75, v223
	s_mov_b64 s[24:25], -1
	s_and_b64 vcc, exec, s[4:5]
	v_pk_add_f32 v[62:63], v[62:63], v[70:71]
	v_pk_add_f32 v[60:61], v[60:61], v[68:69]
	v_pk_add_f32 v[58:59], v[58:59], v[74:75]
	v_pk_add_f32 v[56:57], v[56:57], v[72:73]
	global_store_dwordx4 v[64:65], v[60:63], off
	global_store_dwordx4 v[64:65], v[56:59], off offset:16
	s_cbranch_vccz .LBB0_752
	s_nop 1
	v_mov_b32_e32 v68, v224
	v_mov_b32_e32 v69, v225
	v_mov_b32_e32 v70, v226
	v_mov_b32_e32 v71, v227
	s_nop 1
	v_mov_b32_e32 v72, v228
	v_mov_b32_e32 v73, v229
	v_mov_b32_e32 v74, v230
	v_mov_b32_e32 v75, v231
	s_mov_b64 s[24:25], 0
	v_pk_add_f32 v[70:71], v[54:55], v[70:71]
	v_pk_add_f32 v[68:69], v[52:53], v[68:69]
	v_pk_add_f32 v[74:75], v[50:51], v[74:75]
	v_pk_add_f32 v[72:73], v[48:49], v[72:73]
	global_store_dwordx4 v[64:65], v[68:71], off offset:512
	global_store_dwordx4 v[64:65], v[72:75], off offset:528
.LBB0_752:
	s_andn2_b64 vcc, exec, s[24:25]
	s_cbranch_vccnz .LBB0_756
	v_cvt_pk_bf16_f32 v68, v60, v61
	v_mul_f32_e32 v61, v61, v61
	v_fmac_f32_e32 v61, v60, v60
	v_mul_f32_e32 v60, v63, v63
	v_cvt_pk_bf16_f32 v70, v56, v57
	v_fmac_f32_e32 v60, v62, v62
	v_mul_f32_e32 v57, v57, v57
	v_add_f32_e32 v60, v61, v60
	v_fmac_f32_e32 v57, v56, v56
	v_cvt_pk_bf16_f32 v69, v62, v63
	v_cvt_pk_bf16_f32 v71, v58, v59
	v_lshl_add_u64 v[66:67], v[66:67], 1, s[10:11]
	v_add_f32_e32 v56, v60, v57
	v_mul_f32_e32 v57, v59, v59
	global_store_dwordx4 v[66:67], v[68:71], off
	v_fmac_f32_e32 v57, v58, v58
	s_nop 0
	v_add_f32_e32 v68, v57, v56
	s_nop 1
	v_mov_b32_e32 v56, v228
	v_mov_b32_e32 v57, v229
	v_mov_b32_e32 v58, v230
	v_mov_b32_e32 v59, v231
	s_nop 1
	v_mov_b32_e32 v60, v224
	v_mov_b32_e32 v61, v225
	v_mov_b32_e32 v62, v226
	v_mov_b32_e32 v63, v227
	v_pk_add_f32 v[50:51], v[50:51], v[58:59]
	v_pk_add_f32 v[54:55], v[54:55], v[62:63]
	v_pk_add_f32 v[52:53], v[52:53], v[60:61]
	v_pk_add_f32 v[48:49], v[48:49], v[56:57]
	global_store_dwordx4 v[64:65], v[52:55], off offset:512
	global_store_dwordx4 v[64:65], v[48:51], off offset:528
	v_cvt_pk_bf16_f32 v59, v50, v51
	v_cvt_pk_bf16_f32 v56, v52, v53
	v_mul_f32_e32 v51, v51, v51
	v_fmac_f32_e32 v51, v50, v50
	v_mul_f32_e32 v50, v53, v53
	v_fmac_f32_e32 v50, v52, v52
	v_mul_f32_e32 v52, v55, v55
	v_cvt_pk_bf16_f32 v58, v48, v49
	v_fmac_f32_e32 v52, v54, v54
	v_mul_f32_e32 v49, v49, v49
	v_add_f32_e32 v50, v50, v52
	v_fmac_f32_e32 v49, v48, v48
	v_add_f32_e32 v48, v50, v49
	v_add_f32_e32 v48, v51, v48
	v_add_f32_e32 v48, v68, v48
	ds_bpermute_b32 v49, v180, v48
	v_cvt_pk_bf16_f32 v57, v54, v55
	global_store_dwordx4 v[66:67], v[56:59], off offset:256
	s_waitcnt lgkmcnt(0)
	v_add_f32_e32 v48, v48, v49
	ds_bpermute_b32 v49, v181, v48
	s_and_saveexec_b64 s[24:25], s[6:7]
	s_cbranch_execz .LBB0_755
	s_waitcnt lgkmcnt(0)
	v_add_f32_e32 v48, v48, v49
	v_fma_f32 v48, v48, s65, 0.5
	v_trunc_f32_e32 v48, v48
	v_mul_f32_e32 v49, 0x2f800000, v48
	v_floor_f32_e32 v49, v49
	v_fmac_f32_e32 v48, 0xcf800000, v49
	v_cvt_u32_f32_e32 v48, v48
	v_cvt_u32_f32_e32 v49, v49
	v_lshl_add_u64 v[50:51], v[138:139], 3, s[14:15]
	global_atomic_add_x2 v[50:51], v[48:49], off offset:1024

.LBB0_756:
	s_mov_b64 s[24:25], 0x24000
	v_lshl_add_u64 v[50:51], v[140:141], 0, s[24:25]
	s_waitcnt lgkmcnt(0)
	v_lshl_add_u64 v[48:49], v[50:51], 2, s[12:13]
	s_mov_b64 s[98:99], 0xb0000
	v_lshl_add_u64 v[250:251], v[248:249], 0, s[98:99]
	global_load_dwordx4 v[216:219], v[250:251], off
	global_load_dwordx4 v[220:223], v[250:251], off offset:16
	global_load_dwordx4 v[224:227], v[250:251], off offset:512
	global_load_dwordx4 v[228:231], v[250:251], off offset:528
	s_waitcnt vmcnt(16)
	s_nop 1
	v_mov_b32_e32 v52, v232
	v_mov_b32_e32 v53, v233
	v_mov_b32_e32 v54, v234
	v_mov_b32_e32 v55, v235
	s_nop 1
	v_mov_b32_e32 v56, v236
	v_mov_b32_e32 v57, v237
	v_mov_b32_e32 v58, v238
	v_mov_b32_e32 v59, v239
	s_mov_b64 s[24:25], -1
	s_and_b64 vcc, exec, s[4:5]
	v_pk_add_f32 v[46:47], v[46:47], v[54:55]
	v_pk_add_f32 v[44:45], v[44:45], v[52:53]
	v_pk_add_f32 v[42:43], v[42:43], v[58:59]
	v_pk_add_f32 v[40:41], v[40:41], v[56:57]
	global_store_dwordx4 v[48:49], v[44:47], off
	global_store_dwordx4 v[48:49], v[40:43], off offset:16
	s_cbranch_vccz .LBB0_758
	s_nop 1
	v_mov_b32_e32 v52, v240
	v_mov_b32_e32 v53, v241
	v_mov_b32_e32 v54, v242
	v_mov_b32_e32 v55, v243
	s_nop 1
	v_mov_b32_e32 v56, v244
	v_mov_b32_e32 v57, v245
	v_mov_b32_e32 v58, v246
	v_mov_b32_e32 v59, v247
	s_mov_b64 s[24:25], 0
	v_pk_add_f32 v[54:55], v[38:39], v[54:55]
	v_pk_add_f32 v[52:53], v[36:37], v[52:53]
	v_pk_add_f32 v[58:59], v[34:35], v[58:59]
	v_pk_add_f32 v[56:57], v[32:33], v[56:57]
	global_store_dwordx4 v[48:49], v[52:55], off offset:512
	global_store_dwordx4 v[48:49], v[56:59], off offset:528
.LBB0_758:
	s_andn2_b64 vcc, exec, s[24:25]
	s_cbranch_vccnz .LBB0_762
	v_cvt_pk_bf16_f32 v52, v44, v45
	v_mul_f32_e32 v45, v45, v45
	v_fmac_f32_e32 v45, v44, v44
	v_mul_f32_e32 v44, v47, v47
	v_cvt_pk_bf16_f32 v54, v40, v41
	v_fmac_f32_e32 v44, v46, v46
	v_mul_f32_e32 v41, v41, v41
	v_add_f32_e32 v44, v45, v44
	v_fmac_f32_e32 v41, v40, v40
	v_cvt_pk_bf16_f32 v53, v46, v47
	v_cvt_pk_bf16_f32 v55, v42, v43
	v_lshl_add_u64 v[50:51], v[50:51], 1, s[10:11]
	v_add_f32_e32 v40, v44, v41
	v_mul_f32_e32 v41, v43, v43
	global_store_dwordx4 v[50:51], v[52:55], off
	v_fmac_f32_e32 v41, v42, v42
	s_nop 0
	v_add_f32_e32 v52, v41, v40
	s_nop 1
	v_mov_b32_e32 v40, v244
	v_mov_b32_e32 v41, v245
	v_mov_b32_e32 v42, v246
	v_mov_b32_e32 v43, v247
	s_nop 1
	v_mov_b32_e32 v44, v240
	v_mov_b32_e32 v45, v241
	v_mov_b32_e32 v46, v242
	v_mov_b32_e32 v47, v243
	v_pk_add_f32 v[34:35], v[34:35], v[42:43]
	v_pk_add_f32 v[38:39], v[38:39], v[46:47]
	v_pk_add_f32 v[36:37], v[36:37], v[44:45]
	v_pk_add_f32 v[32:33], v[32:33], v[40:41]
	global_store_dwordx4 v[48:49], v[36:39], off offset:512
	global_store_dwordx4 v[48:49], v[32:35], off offset:528
	v_cvt_pk_bf16_f32 v43, v34, v35
	v_cvt_pk_bf16_f32 v40, v36, v37
	v_mul_f32_e32 v35, v35, v35
	v_fmac_f32_e32 v35, v34, v34
	v_mul_f32_e32 v34, v37, v37
	v_fmac_f32_e32 v34, v36, v36
	v_mul_f32_e32 v36, v39, v39
	v_cvt_pk_bf16_f32 v42, v32, v33
	v_fmac_f32_e32 v36, v38, v38
	v_mul_f32_e32 v33, v33, v33
	v_add_f32_e32 v34, v34, v36
	v_fmac_f32_e32 v33, v32, v32
	v_add_f32_e32 v32, v34, v33
	v_add_f32_e32 v32, v35, v32
	v_add_f32_e32 v32, v52, v32
	ds_bpermute_b32 v33, v180, v32
	v_cvt_pk_bf16_f32 v41, v38, v39
	global_store_dwordx4 v[50:51], v[40:43], off offset:256
	s_waitcnt lgkmcnt(0)
	v_add_f32_e32 v32, v32, v33
	ds_bpermute_b32 v33, v181, v32
	s_and_saveexec_b64 s[24:25], s[6:7]
	s_cbranch_execz .LBB0_761
	s_waitcnt lgkmcnt(0)
	v_add_f32_e32 v32, v32, v33
	v_fma_f32 v32, v32, s65, 0.5
	v_trunc_f32_e32 v32, v32
	v_mul_f32_e32 v33, 0x2f800000, v32
	v_floor_f32_e32 v33, v33
	v_fmac_f32_e32 v32, 0xcf800000, v33
	v_cvt_u32_f32_e32 v32, v32
	v_cvt_u32_f32_e32 v33, v33
	v_lshl_add_u64 v[34:35], v[138:139], 3, s[14:15]
	global_atomic_add_x2 v[34:35], v[32:33], off offset:1152

.LBB0_762:
	s_mov_b64 s[24:25], 0x28000
	v_lshl_add_u64 v[34:35], v[140:141], 0, s[24:25]
	s_waitcnt lgkmcnt(0)
	v_lshl_add_u64 v[32:33], v[34:35], 2, s[12:13]
	s_waitcnt vmcnt(12)
	s_nop 1
	v_mov_b32_e32 v36, v200
	v_mov_b32_e32 v37, v201
	v_mov_b32_e32 v38, v202
	v_mov_b32_e32 v39, v203
	s_nop 1
	v_mov_b32_e32 v40, v204
	v_mov_b32_e32 v41, v205
	v_mov_b32_e32 v42, v206
	v_mov_b32_e32 v43, v207
	s_mov_b64 s[24:25], -1
	s_and_b64 vcc, exec, s[4:5]
	v_pk_add_f32 v[30:31], v[30:31], v[38:39]
	v_pk_add_f32 v[28:29], v[28:29], v[36:37]
	v_pk_add_f32 v[26:27], v[26:27], v[42:43]
	v_pk_add_f32 v[24:25], v[24:25], v[40:41]
	global_store_dwordx4 v[32:33], v[28:31], off
	global_store_dwordx4 v[32:33], v[24:27], off offset:16
	s_cbranch_vccz .LBB0_764
	s_nop 1
	v_mov_b32_e32 v36, v208
	v_mov_b32_e32 v37, v209
	v_mov_b32_e32 v38, v210
	v_mov_b32_e32 v39, v211
	s_nop 1
	v_mov_b32_e32 v40, v212
	v_mov_b32_e32 v41, v213
	v_mov_b32_e32 v42, v214
	v_mov_b32_e32 v43, v215
	s_mov_b64 s[24:25], 0
	v_pk_add_f32 v[38:39], v[22:23], v[38:39]
	v_pk_add_f32 v[36:37], v[20:21], v[36:37]
	v_pk_add_f32 v[42:43], v[18:19], v[42:43]
	v_pk_add_f32 v[40:41], v[16:17], v[40:41]
	global_store_dwordx4 v[32:33], v[36:39], off offset:512
	global_store_dwordx4 v[32:33], v[40:43], off offset:528
.LBB0_764:
	s_andn2_b64 vcc, exec, s[24:25]
	s_cbranch_vccnz .LBB0_768
	v_cvt_pk_bf16_f32 v36, v28, v29
	v_mul_f32_e32 v29, v29, v29
	v_fmac_f32_e32 v29, v28, v28
	v_mul_f32_e32 v28, v31, v31
	v_cvt_pk_bf16_f32 v38, v24, v25
	v_fmac_f32_e32 v28, v30, v30
	v_mul_f32_e32 v25, v25, v25
	v_add_f32_e32 v28, v29, v28
	v_fmac_f32_e32 v25, v24, v24
	v_cvt_pk_bf16_f32 v37, v30, v31
	v_cvt_pk_bf16_f32 v39, v26, v27
	v_lshl_add_u64 v[34:35], v[34:35], 1, s[10:11]
	v_add_f32_e32 v24, v28, v25
	v_mul_f32_e32 v25, v27, v27
	global_store_dwordx4 v[34:35], v[36:39], off
	v_fmac_f32_e32 v25, v26, v26
	s_nop 0
	v_add_f32_e32 v36, v25, v24
	s_nop 1
	v_mov_b32_e32 v24, v212
	v_mov_b32_e32 v25, v213
	v_mov_b32_e32 v26, v214
	v_mov_b32_e32 v27, v215
	s_nop 1
	v_mov_b32_e32 v28, v208
	v_mov_b32_e32 v29, v209
	v_mov_b32_e32 v30, v210
	v_mov_b32_e32 v31, v211
	v_pk_add_f32 v[18:19], v[18:19], v[26:27]
	v_pk_add_f32 v[22:23], v[22:23], v[30:31]
	v_pk_add_f32 v[20:21], v[20:21], v[28:29]
	v_pk_add_f32 v[16:17], v[16:17], v[24:25]
	global_store_dwordx4 v[32:33], v[20:23], off offset:512
	global_store_dwordx4 v[32:33], v[16:19], off offset:528
	v_cvt_pk_bf16_f32 v27, v18, v19
	v_cvt_pk_bf16_f32 v24, v20, v21
	v_mul_f32_e32 v19, v19, v19
	v_fmac_f32_e32 v19, v18, v18
	v_mul_f32_e32 v18, v21, v21
	v_fmac_f32_e32 v18, v20, v20
	v_mul_f32_e32 v20, v23, v23
	v_cvt_pk_bf16_f32 v26, v16, v17
	v_fmac_f32_e32 v20, v22, v22
	v_mul_f32_e32 v17, v17, v17
	v_add_f32_e32 v18, v18, v20
	v_fmac_f32_e32 v17, v16, v16
	v_add_f32_e32 v16, v18, v17
	v_add_f32_e32 v16, v19, v16
	v_add_f32_e32 v16, v36, v16
	ds_bpermute_b32 v17, v180, v16
	v_cvt_pk_bf16_f32 v25, v22, v23
	global_store_dwordx4 v[34:35], v[24:27], off offset:256
	s_waitcnt lgkmcnt(0)
	v_add_f32_e32 v16, v16, v17
	ds_bpermute_b32 v17, v181, v16
	s_and_saveexec_b64 s[24:25], s[6:7]
	s_cbranch_execz .LBB0_767
	s_waitcnt lgkmcnt(0)
	v_add_f32_e32 v16, v16, v17
	v_fma_f32 v16, v16, s65, 0.5
	v_trunc_f32_e32 v16, v16
	v_mul_f32_e32 v17, 0x2f800000, v16
	v_floor_f32_e32 v17, v17
	v_fmac_f32_e32 v16, 0xcf800000, v17
	v_cvt_u32_f32_e32 v16, v16
	v_cvt_u32_f32_e32 v17, v17
	v_lshl_add_u64 v[18:19], v[138:139], 3, s[14:15]
	global_atomic_add_x2 v[18:19], v[16:17], off offset:1280

.LBB0_768:
	s_mov_b64 s[24:25], 0x2c000
	v_lshl_add_u64 v[18:19], v[140:141], 0, s[24:25]
	s_waitcnt lgkmcnt(0)
	v_lshl_add_u64 v[16:17], v[18:19], 2, s[12:13]
	s_waitcnt vmcnt(8)
	s_nop 1
	v_mov_b32_e32 v20, v216
	v_mov_b32_e32 v21, v217
	v_mov_b32_e32 v22, v218
	v_mov_b32_e32 v23, v219
	s_nop 1
	v_mov_b32_e32 v24, v220
	v_mov_b32_e32 v25, v221
	v_mov_b32_e32 v26, v222
	v_mov_b32_e32 v27, v223
	s_mov_b64 s[24:25], -1
	s_and_b64 vcc, exec, s[4:5]
	v_pk_add_f32 v[14:15], v[14:15], v[22:23]
	v_pk_add_f32 v[12:13], v[12:13], v[20:21]
	v_pk_add_f32 v[10:11], v[10:11], v[26:27]
	v_pk_add_f32 v[8:9], v[8:9], v[24:25]
	global_store_dwordx4 v[16:17], v[12:15], off
	global_store_dwordx4 v[16:17], v[8:11], off offset:16
	s_cbranch_vccz .LBB0_770
	s_nop 1
	v_mov_b32_e32 v20, v224
	v_mov_b32_e32 v21, v225
	v_mov_b32_e32 v22, v226
	v_mov_b32_e32 v23, v227
	s_nop 1
	v_mov_b32_e32 v24, v228
	v_mov_b32_e32 v25, v229
	v_mov_b32_e32 v26, v230
	v_mov_b32_e32 v27, v231
	s_mov_b64 s[24:25], 0
	v_pk_add_f32 v[22:23], v[6:7], v[22:23]
	v_pk_add_f32 v[20:21], v[4:5], v[20:21]
	v_pk_add_f32 v[26:27], v[2:3], v[26:27]
	v_pk_add_f32 v[24:25], v[0:1], v[24:25]
	global_store_dwordx4 v[16:17], v[20:23], off offset:512
	global_store_dwordx4 v[16:17], v[24:27], off offset:528
.LBB0_770:
	s_andn2_b64 vcc, exec, s[24:25]
	s_cbranch_vccnz .LBB0_717
	v_cvt_pk_bf16_f32 v20, v12, v13
	v_mul_f32_e32 v13, v13, v13
	v_fmac_f32_e32 v13, v12, v12
	v_mul_f32_e32 v12, v15, v15
	v_cvt_pk_bf16_f32 v22, v8, v9
	v_fmac_f32_e32 v12, v14, v14
	v_mul_f32_e32 v9, v9, v9
	v_add_f32_e32 v12, v13, v12
	v_fmac_f32_e32 v9, v8, v8
	v_cvt_pk_bf16_f32 v21, v14, v15
	v_cvt_pk_bf16_f32 v23, v10, v11
	v_lshl_add_u64 v[18:19], v[18:19], 1, s[10:11]
	v_add_f32_e32 v8, v12, v9
	v_mul_f32_e32 v9, v11, v11
	global_store_dwordx4 v[18:19], v[20:23], off
	v_fmac_f32_e32 v9, v10, v10
	s_nop 0
	v_add_f32_e32 v20, v9, v8
	s_nop 1
	v_mov_b32_e32 v8, v228
	v_mov_b32_e32 v9, v229
	v_mov_b32_e32 v10, v230
	v_mov_b32_e32 v11, v231
	s_nop 1
	v_mov_b32_e32 v12, v224
	v_mov_b32_e32 v13, v225
	v_mov_b32_e32 v14, v226
	v_mov_b32_e32 v15, v227
	v_pk_add_f32 v[2:3], v[2:3], v[10:11]
	v_pk_add_f32 v[6:7], v[6:7], v[14:15]
	v_pk_add_f32 v[4:5], v[4:5], v[12:13]
	v_pk_add_f32 v[0:1], v[0:1], v[8:9]
	global_store_dwordx4 v[16:17], v[4:7], off offset:512
	global_store_dwordx4 v[16:17], v[0:3], off offset:528
	v_cvt_pk_bf16_f32 v11, v2, v3
	v_cvt_pk_bf16_f32 v8, v4, v5
	v_mul_f32_e32 v3, v3, v3
	v_fmac_f32_e32 v3, v2, v2
	v_mul_f32_e32 v2, v5, v5
	v_fmac_f32_e32 v2, v4, v4
	v_mul_f32_e32 v4, v7, v7
	v_cvt_pk_bf16_f32 v10, v0, v1
	v_fmac_f32_e32 v4, v6, v6
	v_mul_f32_e32 v1, v1, v1
	v_add_f32_e32 v2, v2, v4
	v_fmac_f32_e32 v1, v0, v0
	v_add_f32_e32 v0, v2, v1
	v_add_f32_e32 v0, v3, v0
	v_add_f32_e32 v0, v20, v0
	ds_bpermute_b32 v1, v180, v0
	v_cvt_pk_bf16_f32 v9, v6, v7
	global_store_dwordx4 v[18:19], v[8:11], off offset:256
	s_waitcnt lgkmcnt(0)
	v_add_f32_e32 v0, v0, v1
	ds_bpermute_b32 v1, v181, v0
	s_and_saveexec_b64 s[24:25], s[6:7]
	s_cbranch_execz .LBB0_716
	s_waitcnt lgkmcnt(0)
	v_add_f32_e32 v0, v0, v1
	v_fma_f32 v0, v0, s65, 0.5
	v_trunc_f32_e32 v0, v0
	v_mul_f32_e32 v1, 0x2f800000, v0
	v_floor_f32_e32 v1, v1
	v_fmac_f32_e32 v0, 0xcf800000, v1
	v_cvt_u32_f32_e32 v0, v0
	v_cvt_u32_f32_e32 v1, v1
	v_lshl_add_u64 v[2:3], v[138:139], 3, s[14:15]
	global_atomic_add_x2 v[2:3], v[0:1], off offset:1408
	s_branch .LBB0_716
